# epilogue peephole: fold v_mov + in-place DPP rotate into one DPP mov (272 sites in FFN-up epilogue, 68 in even in-proj epilogue), hazard-checked
# speedup vs baseline: 1.0132x; 1.0122x over previous
; #define LAS __attribute__((address_space(3)))
;     __device__ __forceinline__ void operator()(f32x4 (&acc)[2][2][4][2], const Unit& u, int wr, int wc, int fr, int fq) const {
;     ...
;         asm volatile("s_waitcnt lgkmcnt(0)" ::: "memory"); __builtin_amdgcn_s_barrier(); asm volatile("" ::: "memory");
;         const f32x4 w0 = *(const f32x4*)(cw + ch), w1 = *(const f32x4*)(cw + 512 + ch), w2 = *(const f32x4*)(cw + 1024 + ch);
;         const bool seq0 = (u.pm & 15) == 0;
; #pragma unroll
;         for (int ai = 0; ai < 2; ++ai)
; #pragma unroll
;             for (int m = 0; m < 4; ++m) {
;                 const f32x4 cur = acc[ai][0][m][0]; f32x4 p1 = ror4(cur, 1), p2 = ror4(cur, 2);
;                 if (m > 0) { const f32x4 pv = acc[ai][0][m - 1][0]; const f32x4 q1 = ror4(pv, 1), q2 = ror4(pv, 2);
; #pragma unroll
;                     for (int e = 0; e < 4; ++e) { p1[e] = (fr == 0) ? q1[e] : p1[e]; p2[e] = (fr < 2) ? q2[e] : p2[e]; } }
;                 else { f32x4 h14 = (f32x4){0.f, 0.f, 0.f, 0.f}, h15 = h14;
;                     if (!(wr == 0 && ai == 0)) { const int sai = (wr == 1) ? ai : 0, swr = (wr == 1) ? 0 : 1; const LAS float* hp = hl + ((((sai * 2 + swr) * 4 + wc) * 2 + 0) * 16 + fq * 4);
;                         h14 = *(const LAS f32x4*)hp; h15 = *(const LAS f32x4*)(hp + 16); }
; #pragma unroll
;                     for (int e = 0; e < 4; ++e) { p1[e] = (fr == 0) ? h15[e] : p1[e]; p2[e] = (fr == 0) ? h14[e] : ((fr == 1) ? h15[e] : p2[e]); } }
.LBB0_592:
	s_or_b64 exec, exec, s[90:91]
	v_lshlrev_b64 v[68:69], 2, v[130:131]
	s_waitcnt lgkmcnt(0)
	s_barrier
	v_lshl_add_u64 v[70:71], s[2:3], 0, v[68:69]
	v_lshl_add_u64 v[68:69], s[16:17], 0, v[68:69]
	global_load_dwordx4 v[76:79], v[70:71], off
	global_load_dwordx4 v[72:75], v[70:71], off offset:2048
	v_mov_b32_dpp v123, v80 row_ror:1 row_mask:0xf bank_mask:0xf
	global_load_dwordx4 v[68:71], v[68:69], off
	v_mov_b32_dpp v119, v81 row_ror:1 row_mask:0xf bank_mask:0xf
	v_mov_b32_dpp v113, v82 row_ror:1 row_mask:0xf bank_mask:0xf
	v_mov_b32_dpp v111, v83 row_ror:1 row_mask:0xf bank_mask:0xf
	v_mov_b32_dpp v136, v80 row_ror:2 row_mask:0xf bank_mask:0xf
	v_mov_b32_dpp v135, v81 row_ror:2 row_mask:0xf bank_mask:0xf
	v_mov_b32_dpp v129, v82 row_ror:2 row_mask:0xf bank_mask:0xf
	v_mov_b32_dpp v127, v83 row_ror:2 row_mask:0xf bank_mask:0xf
	v_mov_b32_e32 v92, 0
	s_andn2_b64 vcc, exec, s[14:15]
	v_mov_b32_e32 v93, 0
	v_mov_b32_e32 v94, 0
	v_mov_b32_e32 v95, 0
	v_mov_b32_e32 v96, 0
	v_mov_b32_e32 v97, 0
	v_mov_b32_e32 v98, 0
	v_mov_b32_e32 v99, 0
	s_cbranch_vccnz .LBB0_594
	v_lshl_add_u32 v96, v128, 2, s66
	ds_read_b128 v[92:95], v96
	ds_read_b128 v[96:99], v96 offset:64

;     __device__ __forceinline__ void operator()(f32x4 (&acc)[2][2][4][2], const Unit& u, int wr, int wc, int fr, int fq) const {
;     ...
;         EPI_FOR_ROWS() { const int row = row0 + ai * 128 + m * 16; const float rs = row_rstd(ssq, row, fq);
;             acc[ai][0][m][0] = (acc[ai][0][m][0] * rs) * (acc[ai][0][m][1] * rs); acc[ai][1][m][0] *= rs;
;             const f32x4 uu = acc[ai][1][m][1] * rs; u32x2 w; w.x = cvt_pk_bf16(uu[0], uu[1]); w.y = cvt_pk_bf16(uu[2], uu[3]);
;             *(u32x2*)(a2 + ((size_t)(ch >> 4) * 2048 + (row >> 4)) * 384 + (row & 15) * 16 + (ch & 15)) = w; }
;         if (fr >= 14) {
; #pragma unroll
;             for (int ai = 0; ai < 2; ++ai) *(LAS f32x4*)(hl + ((((ai * 2 + wr) * 4 + wc) * 2 + (fr - 14)) * 16 + fq * 4)) = acc[ai][0][3][0];
;             if (wr == 1) *(f32x4*)(tail + ((size_t)u.pm * 2 + (fr - 14)) * 512 + ch) = acc[1][0][3][0]; }
;         if (wr == 0 && fr < 2) { *(f32x4*)(head + (((size_t)u.pm * 2 + fr) * 2 + 0) * 512 + ch) = acc[0][0][0][0]; *(f32x4*)(head + (((size_t)u.pm * 2 + fr) * 2 + 1) * 512 + ch) = acc[0][1][0][0]; }
;         asm volatile("s_waitcnt lgkmcnt(0)" ::: "memory"); __builtin_amdgcn_s_barrier(); asm volatile("" ::: "memory");
;         const f32x4 w0 = *(const f32x4*)(cw + ch), w1 = *(const f32x4*)(cw + 512 + ch), w2 = *(const f32x4*)(cw + 1024 + ch);
;         const bool seq0 = (u.pm & 15) == 0;
; #pragma unroll
;         for (int ai = 0; ai < 2; ++ai)
; #pragma unroll
;             for (int m = 0; m < 4; ++m) {
;                 const f32x4 cur = acc[ai][0][m][0]; f32x4 p1 = ror4(cur, 1), p2 = ror4(cur, 2);
;                 if (m > 0) { const f32x4 pv = acc[ai][0][m - 1][0]; const f32x4 q1 = ror4(pv, 1), q2 = ror4(pv, 2);
; #pragma unroll
;                     for (int e = 0; e < 4; ++e) { p1[e] = (fr == 0) ? q1[e] : p1[e]; p2[e] = (fr < 2) ? q2[e] : p2[e]; } }
;                 else { f32x4 h14 = (f32x4){0.f, 0.f, 0.f, 0.f}, h15 = h14;
;                     if (!(wr == 0 && ai == 0)) { const int sai = (wr == 1) ? ai : 0, swr = (wr == 1) ? 0 : 1; const LAS float* hp = hl + ((((sai * 2 + swr) * 4 + wc) * 2 + 0) * 16 + fq * 4);
;                         h14 = *(const LAS f32x4*)hp; h15 = *(const LAS f32x4*)(hp + 16); }
; #pragma unroll
;                     for (int e = 0; e < 4; ++e) { p1[e] = (fr == 0) ? h15[e] : p1[e]; p2[e] = (fr == 0) ? h14[e] : ((fr == 1) ? h15[e] : p2[e]); } }
.LBB0_596:
	s_or_b64 exec, exec, s[84:85]
	v_mov_b32_e32 v127, v126
	v_mov_b32_e32 v123, v122
	v_pk_mul_f32 v[64:65], v[64:65], v[126:127]
	v_pk_mul_f32 v[60:61], v[60:61], v[126:127]
	v_pk_mul_f32 v[56:57], v[56:57], v[122:123]
	v_pk_mul_f32 v[52:53], v[52:53], v[122:123]
	v_pk_mul_f32 v[60:61], v[64:65], v[60:61]
	v_mov_b32_e32 v64, v122
	v_mov_b32_e32 v65, v122
	v_pk_mul_f32 v[52:53], v[56:57], v[52:53]
	v_mov_b32_e32 v56, v118
	v_mov_b32_e32 v57, v118
	v_mov_b32_e32 v111, v110
	v_mov_b32_e32 v88, v126
	v_mov_b32_e32 v89, v126
	v_pk_mul_f32 v[58:59], v[58:59], v[64:65]
	v_pk_mul_f32 v[54:55], v[54:55], v[64:65]
	v_pk_mul_f32 v[42:43], v[42:43], v[56:57]
	v_mov_b32_e32 v56, v110
	v_mov_b32_e32 v57, v110
	v_mov_b32_e32 v113, v112
	v_pk_mul_f32 v[66:67], v[66:67], v[88:89]
	v_pk_mul_f32 v[62:63], v[62:63], v[88:89]
	v_pk_mul_f32 v[54:55], v[58:59], v[54:55]
	v_pk_mul_f32 v[38:39], v[38:39], v[56:57]
	v_pk_mul_f32 v[36:37], v[36:37], v[110:111]
	v_pk_mul_f32 v[34:35], v[34:35], v[56:57]
	v_pk_mul_f32 v[58:59], v[32:33], v[110:111]
	v_mov_b32_e32 v147, v146
	v_pk_mul_f32 v[62:63], v[66:67], v[62:63]
	v_pk_mul_f32 v[32:33], v[38:39], v[34:35]
	v_pk_mul_f32 v[34:35], v[36:37], v[58:59]
	v_pk_mul_f32 v[36:37], v[22:23], v[56:57]
	v_mov_b32_e32 v56, v112
	v_mov_b32_e32 v57, v112
	v_pk_mul_f32 v[22:23], v[28:29], v[112:113]
	v_pk_mul_f32 v[24:25], v[24:25], v[112:113]
	v_pk_mul_f32 v[38:39], v[20:21], v[110:111]
	v_pk_mul_f32 v[20:21], v[30:31], v[56:57]
	v_pk_mul_f32 v[26:27], v[26:27], v[56:57]
	v_pk_mul_f32 v[22:23], v[22:23], v[24:25]
	v_pk_mul_f32 v[24:25], v[10:11], v[56:57]
	v_mov_b32_e32 v28, v146
	v_mov_b32_e32 v29, v146
	v_pk_mul_f32 v[10:11], v[16:17], v[146:147]
	v_pk_mul_f32 v[12:13], v[12:13], v[146:147]
	v_mov_b32_dpp v56, v60 row_ror:2 row_mask:0xf bank_mask:0xf
	v_mov_b32_dpp v57, v61 row_ror:2 row_mask:0xf bank_mask:0xf
	v_mov_b32_dpp v58, v62 row_ror:2 row_mask:0xf bank_mask:0xf
	v_mov_b32_dpp v59, v63 row_ror:2 row_mask:0xf bank_mask:0xf
	v_pk_mul_f32 v[46:47], v[46:47], v[64:65]
	v_pk_mul_f32 v[20:21], v[20:21], v[26:27]
	v_pk_mul_f32 v[26:27], v[8:9], v[112:113]
	v_pk_mul_f32 v[8:9], v[18:19], v[28:29]
	v_pk_mul_f32 v[14:15], v[14:15], v[28:29]
	v_pk_mul_f32 v[10:11], v[10:11], v[12:13]
	v_pk_mul_f32 v[6:7], v[6:7], v[28:29]
	v_mov_b32_e32 v12, v140
	v_mov_b32_e32 v13, v140
	v_mov_b32_dpp v28, v60 row_ror:1 row_mask:0xf bank_mask:0xf
	v_mov_b32_dpp v29, v61 row_ror:1 row_mask:0xf bank_mask:0xf
	v_mov_b32_dpp v30, v62 row_ror:1 row_mask:0xf bank_mask:0xf
	v_mov_b32_dpp v31, v63 row_ror:1 row_mask:0xf bank_mask:0xf
	v_mov_b32_dpp v16, v80 row_ror:1 row_mask:0xf bank_mask:0xf
	v_mov_b32_dpp v19, v81 row_ror:1 row_mask:0xf bank_mask:0xf
	v_mov_b32_dpp v64, v82 row_ror:1 row_mask:0xf bank_mask:0xf
	v_mov_b32_dpp v17, v83 row_ror:1 row_mask:0xf bank_mask:0xf
	v_mov_b32_dpp v80, v80 row_ror:2 row_mask:0xf bank_mask:0xf
	v_mov_b32_dpp v81, v81 row_ror:2 row_mask:0xf bank_mask:0xf
	v_mov_b32_dpp v82, v82 row_ror:2 row_mask:0xf bank_mask:0xf
	v_mov_b32_dpp v83, v83 row_ror:2 row_mask:0xf bank_mask:0xf
	v_pk_mul_f32 v[8:9], v[8:9], v[14:15]
	v_pk_mul_f32 v[2:3], v[2:3], v[12:13]
	v_cndmask_b32_e64 v13, v59, v83, s[10:11]
	v_cndmask_b32_e64 v14, v56, v80, s[10:11]
	v_cndmask_b32_e64 v15, v57, v81, s[10:11]
	v_cndmask_b32_e64 v12, v58, v82, s[10:11]
	v_cndmask_b32_e32 v17, v31, v17, vcc
	v_cndmask_b32_e32 v18, v28, v16, vcc
	v_cndmask_b32_e32 v19, v29, v19, vcc
	v_cndmask_b32_e32 v16, v30, v64, vcc
	v_pk_mul_f32 v[12:13], v[78:79], v[12:13]
	v_pk_mul_f32 v[14:15], v[76:77], v[14:15]
	v_pk_fma_f32 v[12:13], v[74:75], v[16:17], v[12:13]
	v_pk_fma_f32 v[14:15], v[72:73], v[18:19], v[14:15]
	v_pk_mul_f32 v[50:51], v[50:51], v[88:89]
	v_pk_mul_f32 v[48:49], v[48:49], v[126:127]
	v_pk_fma_f32 v[12:13], v[62:63], v[70:71], v[12:13]
	v_pk_fma_f32 v[14:15], v[60:61], v[68:69], v[14:15]
	v_pk_mul_f32 v[12:13], v[50:51], v[12:13]
	v_pk_mul_f32 v[14:15], v[48:49], v[14:15]
	v_mov_b32_dpp v60, v52 row_ror:2 row_mask:0xf bank_mask:0xf
	v_cvt_pk_bf16_f32 v14, v14, v15
	v_cvt_pk_bf16_f32 v15, v12, v13
	v_lshlrev_b64 v[12:13], 11, v[124:125]
	v_lshl_add_u64 v[16:17], s[26:27], 0, v[12:13]
	v_lshlrev_b64 v[12:13], 1, v[130:131]
	v_mov_b32_dpp v61, v53 row_ror:2 row_mask:0xf bank_mask:0xf
	v_mov_b32_dpp v62, v54 row_ror:2 row_mask:0xf bank_mask:0xf
	v_mov_b32_dpp v63, v55 row_ror:2 row_mask:0xf bank_mask:0xf
	v_lshl_add_u64 v[16:17], v[16:17], 0, v[12:13]
	v_mov_b32_dpp v48, v52 row_ror:1 row_mask:0xf bank_mask:0xf
	v_mov_b32_dpp v49, v53 row_ror:1 row_mask:0xf bank_mask:0xf
	v_mov_b32_dpp v50, v54 row_ror:1 row_mask:0xf bank_mask:0xf
	v_mov_b32_dpp v51, v55 row_ror:1 row_mask:0xf bank_mask:0xf
	global_store_dwordx2 v[16:17], v[14:15], off
	v_cndmask_b32_e64 v15, v63, v59, s[10:11]
	v_cndmask_b32_e64 v16, v60, v56, s[10:11]
	v_cndmask_b32_e64 v17, v61, v57, s[10:11]
	v_cndmask_b32_e64 v14, v62, v58, s[10:11]
	v_cndmask_b32_e32 v19, v51, v31, vcc
	v_cndmask_b32_e32 v28, v48, v28, vcc
	v_cndmask_b32_e32 v29, v49, v29, vcc
	v_cndmask_b32_e32 v18, v50, v30, vcc
	v_pk_mul_f32 v[14:15], v[78:79], v[14:15]
	v_pk_mul_f32 v[16:17], v[76:77], v[16:17]
	v_pk_fma_f32 v[14:15], v[74:75], v[18:19], v[14:15]
	v_pk_fma_f32 v[16:17], v[72:73], v[28:29], v[16:17]
	v_pk_mul_f32 v[44:45], v[44:45], v[122:123]
	v_pk_fma_f32 v[14:15], v[54:55], v[70:71], v[14:15]
	v_pk_fma_f32 v[16:17], v[52:53], v[68:69], v[16:17]
	v_pk_mul_f32 v[14:15], v[46:47], v[14:15]
	v_pk_mul_f32 v[16:17], v[44:45], v[16:17]
	v_mov_b32_dpp v28, v106 row_ror:2 row_mask:0xf bank_mask:0xf
	v_cvt_pk_bf16_f32 v16, v16, v17
	v_cvt_pk_bf16_f32 v17, v14, v15
	v_lshlrev_b64 v[14:15], 11, v[120:121]
; #define LAS __attribute__((address_space(3)))
; __device__ __forceinline__ unsigned cvt_pk_bf16(float lo, float hi) { unsigned r; asm volatile("v_cvt_pk_bf16_f32 %0, %1, %2" : "=v"(r) : "v"(lo), "v"(hi)); return r; }
;     __device__ __forceinline__ void operator()(f32x4 (&acc)[2][2][4][2], const Unit& u, int wr, int wc, int fr, int fq) const {
;     ...
;                 const f32x4 cur = acc[ai][0][m][0]; f32x4 p1 = ror4(cur, 1), p2 = ror4(cur, 2);
;                 if (m > 0) { const f32x4 pv = acc[ai][0][m - 1][0]; const f32x4 q1 = ror4(pv, 1), q2 = ror4(pv, 2);
; #pragma unroll
;                     for (int e = 0; e < 4; ++e) { p1[e] = (fr == 0) ? q1[e] : p1[e]; p2[e] = (fr < 2) ? q2[e] : p2[e]; } }
;                 else { f32x4 h14 = (f32x4){0.f, 0.f, 0.f, 0.f}, h15 = h14;
;                     if (!(wr == 0 && ai == 0)) { const int sai = (wr == 1) ? ai : 0, swr = (wr == 1) ? 0 : 1; const LAS float* hp = hl + ((((sai * 2 + swr) * 4 + wc) * 2 + 0) * 16 + fq * 4);
;                         h14 = *(const LAS f32x4*)hp; h15 = *(const LAS f32x4*)(hp + 16); }
; #pragma unroll
;                     for (int e = 0; e < 4; ++e) { p1[e] = (fr == 0) ? h15[e] : p1[e]; p2[e] = (fr == 0) ? h14[e] : ((fr == 1) ? h15[e] : p2[e]); } }
;                 const f32x4 ya = acc[ai][1][m][0] * (w0 * p2 + w1 * p1 + w2 * cur);
;                 u32x2 w; w.x = cvt_pk_bf16(ya[0], ya[1]); w.y = cvt_pk_bf16(ya[2], ya[3]);
;                 const bool edge = (wr == 0 && ai == 0 && m == 0 && fr < 2 && !seq0);
;                 if (!edge) *(u32x2*)(mix + (size_t)(row0 + ai * 128 + m * 16) * 1024 + ch) = w;
	v_lshl_add_u64 v[14:15], s[26:27], 0, v[14:15]
	v_lshl_add_u64 v[14:15], v[14:15], 0, v[12:13]
	global_store_dwordx2 v[14:15], v[16:17], off
	v_mov_b32_dpp v14, v104 row_ror:2 row_mask:0xf bank_mask:0xf
	v_mov_b32_dpp v17, v105 row_ror:2 row_mask:0xf bank_mask:0xf
	v_mov_b32_dpp v15, v107 row_ror:2 row_mask:0xf bank_mask:0xf
	v_mov_b32_dpp v18, v104 row_ror:1 row_mask:0xf bank_mask:0xf
	v_mov_b32_dpp v29, v105 row_ror:1 row_mask:0xf bank_mask:0xf
	v_mov_b32_dpp v30, v106 row_ror:1 row_mask:0xf bank_mask:0xf
	v_mov_b32_dpp v19, v107 row_ror:1 row_mask:0xf bank_mask:0xf
	v_cndmask_b32_e64 v15, v15, v63, s[10:11]
	v_cndmask_b32_e64 v16, v14, v60, s[10:11]
	v_cndmask_b32_e64 v17, v17, v61, s[10:11]
	v_cndmask_b32_e64 v14, v28, v62, s[10:11]
	v_cndmask_b32_e32 v19, v19, v51, vcc
	v_cndmask_b32_e32 v28, v18, v48, vcc
	v_cndmask_b32_e32 v29, v29, v49, vcc
	v_cndmask_b32_e32 v18, v30, v50, vcc
	v_pk_mul_f32 v[14:15], v[78:79], v[14:15]
	v_pk_mul_f32 v[16:17], v[76:77], v[16:17]
	v_mov_b32_e32 v119, v118
	v_pk_fma_f32 v[14:15], v[74:75], v[18:19], v[14:15]
	v_pk_fma_f32 v[16:17], v[72:73], v[28:29], v[16:17]
	v_pk_mul_f32 v[40:41], v[40:41], v[118:119]
	v_pk_fma_f32 v[14:15], v[106:107], v[70:71], v[14:15]
	v_pk_fma_f32 v[16:17], v[104:105], v[68:69], v[16:17]
	v_pk_mul_f32 v[14:15], v[42:43], v[14:15]
	v_pk_mul_f32 v[16:17], v[40:41], v[16:17]
	v_lshl_add_u32 v18, v128, 2, v154
	v_cvt_pk_bf16_f32 v16, v16, v17
	v_cvt_pk_bf16_f32 v17, v14, v15
	v_lshlrev_b64 v[14:15], 11, v[116:117]
	v_lshl_add_u64 v[14:15], s[26:27], 0, v[14:15]
	v_lshl_add_u64 v[14:15], v[14:15], 0, v[12:13]
	global_store_dwordx2 v[14:15], v[16:17], off
	ds_read_b128 v[14:17], v18
	ds_read_b128 v[28:31], v18 offset:64
	v_mov_b32_dpp v40, v34 row_ror:1 row_mask:0xf bank_mask:0xf
	v_mov_b32_dpp v44, v34 row_ror:2 row_mask:0xf bank_mask:0xf
	v_mov_b32_dpp v45, v35 row_ror:2 row_mask:0xf bank_mask:0xf
	v_mov_b32_dpp v41, v35 row_ror:1 row_mask:0xf bank_mask:0xf
	v_mov_b32_dpp v42, v32 row_ror:1 row_mask:0xf bank_mask:0xf
	v_mov_b32_dpp v46, v32 row_ror:2 row_mask:0xf bank_mask:0xf
	v_mov_b32_dpp v47, v33 row_ror:2 row_mask:0xf bank_mask:0xf
	s_waitcnt lgkmcnt(0)
; #define LAS __attribute__((address_space(3)))
; __device__ __forceinline__ unsigned cvt_pk_bf16(float lo, float hi) { unsigned r; asm volatile("v_cvt_pk_bf16_f32 %0, %1, %2" : "=v"(r) : "v"(lo), "v"(hi)); return r; }
; #define PG8_BAR __builtin_amdgcn_s_barrier()
; template <class Epi>
; __device__ __forceinline__ void gemm_phase(LAS unsigned char* lds, const Gemm g, const StaticOrder& S, const Epi& E) {
;     ...
;         if (wr == 0) PG8_BAR;
;         E(acc, cur, wr, wc, fr, fq);
;         if (!has_next) break;
; #pragma unroll
;         for (int a = 0; a < 2; ++a)
; #pragma unroll
;             for (int b = 0; b < 2; ++b)
; #pragma unroll
;                 for (int m = 0; m < 4; ++m)
; #pragma unroll
;                     for (int n = 0; n < 2; ++n) acc[a][b][m][n] = (f32x4){0.f, 0.f, 0.f, 0.f};
;         cur = nxt; cA = nA; cB = nB; ++ui;
;         if (wr == 1) PG8_BAR;
;     __device__ __forceinline__ void operator()(f32x4 (&acc)[2][2][4][2], const Unit& u, int wr, int wc, int fr, int fq) const {
;     ...
;                 const f32x4 cur = acc[ai][0][m][0]; f32x4 p1 = ror4(cur, 1), p2 = ror4(cur, 2);
;                 if (m > 0) { const f32x4 pv = acc[ai][0][m - 1][0]; const f32x4 q1 = ror4(pv, 1), q2 = ror4(pv, 2);
; #pragma unroll
;                     for (int e = 0; e < 4; ++e) { p1[e] = (fr == 0) ? q1[e] : p1[e]; p2[e] = (fr < 2) ? q2[e] : p2[e]; } }
;                 else { f32x4 h14 = (f32x4){0.f, 0.f, 0.f, 0.f}, h15 = h14;
;                     if (!(wr == 0 && ai == 0)) { const int sai = (wr == 1) ? ai : 0, swr = (wr == 1) ? 0 : 1; const LAS float* hp = hl + ((((sai * 2 + swr) * 4 + wc) * 2 + 0) * 16 + fq * 4);
;                         h14 = *(const LAS f32x4*)hp; h15 = *(const LAS f32x4*)(hp + 16); }
; #pragma unroll
;                     for (int e = 0; e < 4; ++e) { p1[e] = (fr == 0) ? h15[e] : p1[e]; p2[e] = (fr == 0) ? h14[e] : ((fr == 1) ? h15[e] : p2[e]); } }
;                 const f32x4 ya = acc[ai][1][m][0] * (w0 * p2 + w1 * p1 + w2 * cur);
;                 u32x2 w; w.x = cvt_pk_bf16(ya[0], ya[1]); w.y = cvt_pk_bf16(ya[2], ya[3]);
;                 const bool edge = (wr == 0 && ai == 0 && m == 0 && fr < 2 && !seq0);
;                 if (!edge) *(u32x2*)(mix + (size_t)(row0 + ai * 128 + m * 16) * 1024 + ch) = w;
	v_cndmask_b32_e32 v18, v40, v28, vcc
	v_cndmask_b32_e64 v19, v44, v28, s[12:13]
	v_cndmask_b32_e64 v28, v45, v29, s[12:13]
	v_mov_b32_dpp v43, v33 row_ror:1 row_mask:0xf bank_mask:0xf
	v_cndmask_b32_e32 v14, v19, v14, vcc
	v_cndmask_b32_e32 v19, v41, v29, vcc
	v_cndmask_b32_e32 v15, v28, v15, vcc
	v_cndmask_b32_e32 v28, v42, v30, vcc
	v_cndmask_b32_e64 v29, v46, v30, s[12:13]
	v_cndmask_b32_e64 v30, v47, v31, s[12:13]
	v_cndmask_b32_e32 v16, v29, v16, vcc
	v_cndmask_b32_e32 v17, v30, v17, vcc
	v_cndmask_b32_e32 v29, v43, v31, vcc
	v_pk_mul_f32 v[14:15], v[76:77], v[14:15]
	v_pk_mul_f32 v[16:17], v[78:79], v[16:17]
	v_pk_fma_f32 v[14:15], v[72:73], v[18:19], v[14:15]
	v_pk_fma_f32 v[16:17], v[74:75], v[28:29], v[16:17]
	v_pk_fma_f32 v[14:15], v[34:35], v[68:69], v[14:15]
	v_pk_fma_f32 v[16:17], v[32:33], v[70:71], v[16:17]
	v_pk_mul_f32 v[14:15], v[38:39], v[14:15]
	v_pk_mul_f32 v[16:17], v[36:37], v[16:17]
	v_cvt_pk_bf16_f32 v14, v14, v15
	v_mov_b32_dpp v34, v22 row_ror:2 row_mask:0xf bank_mask:0xf
	v_cvt_pk_bf16_f32 v15, v16, v17
	v_lshlrev_b64 v[16:17], 11, v[108:109]
	v_lshl_add_u64 v[16:17], s[26:27], 0, v[16:17]
	v_mov_b32_dpp v35, v23 row_ror:2 row_mask:0xf bank_mask:0xf
	v_mov_b32_dpp v36, v20 row_ror:2 row_mask:0xf bank_mask:0xf
	v_mov_b32_dpp v37, v21 row_ror:2 row_mask:0xf bank_mask:0xf
	v_lshl_add_u64 v[16:17], v[16:17], 0, v[12:13]
	v_mov_b32_dpp v30, v22 row_ror:1 row_mask:0xf bank_mask:0xf
	v_mov_b32_dpp v31, v23 row_ror:1 row_mask:0xf bank_mask:0xf
	v_mov_b32_dpp v32, v20 row_ror:1 row_mask:0xf bank_mask:0xf
	v_mov_b32_dpp v33, v21 row_ror:1 row_mask:0xf bank_mask:0xf
	global_store_dwordx2 v[16:17], v[14:15], off
	v_cndmask_b32_e64 v15, v37, v47, s[10:11]
	v_cndmask_b32_e64 v16, v34, v44, s[10:11]
	v_cndmask_b32_e64 v17, v35, v45, s[10:11]
	v_cndmask_b32_e64 v14, v36, v46, s[10:11]
	v_cndmask_b32_e32 v19, v33, v43, vcc
	v_cndmask_b32_e32 v28, v30, v40, vcc
	v_cndmask_b32_e32 v29, v31, v41, vcc
	v_cndmask_b32_e32 v18, v32, v42, vcc
	v_pk_mul_f32 v[14:15], v[78:79], v[14:15]
	v_pk_mul_f32 v[16:17], v[76:77], v[16:17]
	v_pk_fma_f32 v[14:15], v[74:75], v[18:19], v[14:15]
	v_pk_fma_f32 v[16:17], v[72:73], v[28:29], v[16:17]
	v_pk_fma_f32 v[14:15], v[20:21], v[70:71], v[14:15]
	v_pk_fma_f32 v[16:17], v[22:23], v[68:69], v[16:17]
	v_pk_mul_f32 v[14:15], v[24:25], v[14:15]
	v_pk_mul_f32 v[16:17], v[26:27], v[16:17]
	v_mov_b32_dpp v26, v10 row_ror:2 row_mask:0xf bank_mask:0xf
	v_cvt_pk_bf16_f32 v16, v16, v17
	v_cvt_pk_bf16_f32 v17, v14, v15
	v_lshlrev_b64 v[14:15], 11, v[100:101]
	v_lshl_add_u64 v[14:15], s[26:27], 0, v[14:15]
	v_mov_b32_dpp v27, v11 row_ror:2 row_mask:0xf bank_mask:0xf
	v_mov_b32_dpp v28, v8 row_ror:2 row_mask:0xf bank_mask:0xf
	v_mov_b32_dpp v29, v9 row_ror:2 row_mask:0xf bank_mask:0xf
	v_lshl_add_u64 v[14:15], v[14:15], 0, v[12:13]
	v_mov_b32_dpp v22, v10 row_ror:1 row_mask:0xf bank_mask:0xf
	v_mov_b32_dpp v23, v11 row_ror:1 row_mask:0xf bank_mask:0xf
	v_mov_b32_dpp v24, v8 row_ror:1 row_mask:0xf bank_mask:0xf
	v_mov_b32_dpp v25, v9 row_ror:1 row_mask:0xf bank_mask:0xf
	global_store_dwordx2 v[14:15], v[16:17], off
	v_cndmask_b32_e64 v15, v29, v37, s[10:11]
	v_cndmask_b32_e64 v16, v26, v34, s[10:11]
	v_cndmask_b32_e64 v17, v27, v35, s[10:11]
	v_cndmask_b32_e64 v14, v28, v36, s[10:11]
	v_cndmask_b32_e32 v19, v25, v33, vcc
	v_cndmask_b32_e32 v20, v22, v30, vcc
	v_cndmask_b32_e32 v21, v23, v31, vcc
	v_cndmask_b32_e32 v18, v24, v32, vcc
	v_pk_mul_f32 v[14:15], v[78:79], v[14:15]
	v_pk_mul_f32 v[16:17], v[76:77], v[16:17]
	v_pk_fma_f32 v[14:15], v[74:75], v[18:19], v[14:15]
	v_pk_fma_f32 v[16:17], v[72:73], v[20:21], v[16:17]
	v_pk_mul_f32 v[4:5], v[4:5], v[146:147]
	v_pk_fma_f32 v[8:9], v[8:9], v[70:71], v[14:15]
	v_pk_fma_f32 v[10:11], v[10:11], v[68:69], v[16:17]
	v_pk_mul_f32 v[6:7], v[6:7], v[8:9]
	v_pk_mul_f32 v[4:5], v[4:5], v[10:11]
	v_mov_b32_dpp v10, v86 row_ror:2 row_mask:0xf bank_mask:0xf
	v_cvt_pk_bf16_f32 v4, v4, v5
	v_cvt_pk_bf16_f32 v5, v6, v7
	v_lshlrev_b64 v[6:7], 11, v[102:103]
	v_lshl_add_u64 v[6:7], s[26:27], 0, v[6:7]
	v_lshl_add_u64 v[6:7], v[6:7], 0, v[12:13]
	global_store_dwordx2 v[6:7], v[4:5], off
	v_mov_b32_dpp v4, v84 row_ror:2 row_mask:0xf bank_mask:0xf
	v_mov_b32_dpp v7, v85 row_ror:2 row_mask:0xf bank_mask:0xf
	v_mov_b32_dpp v5, v87 row_ror:2 row_mask:0xf bank_mask:0xf
	v_mov_b32_dpp v8, v84 row_ror:1 row_mask:0xf bank_mask:0xf
	v_mov_b32_dpp v11, v85 row_ror:1 row_mask:0xf bank_mask:0xf
	v_mov_b32_dpp v14, v86 row_ror:1 row_mask:0xf bank_mask:0xf
	v_mov_b32_dpp v9, v87 row_ror:1 row_mask:0xf bank_mask:0xf
	v_cndmask_b32_e64 v5, v5, v29, s[10:11]
	v_cndmask_b32_e64 v6, v4, v26, s[10:11]
	v_cndmask_b32_e64 v7, v7, v27, s[10:11]
	v_cndmask_b32_e64 v4, v10, v28, s[10:11]
	v_cndmask_b32_e32 v9, v9, v25, vcc
	v_cndmask_b32_e32 v10, v8, v22, vcc
	v_cndmask_b32_e32 v11, v11, v23, vcc
	v_cndmask_b32_e32 v8, v14, v24, vcc
	v_pk_mul_f32 v[4:5], v[78:79], v[4:5]
	v_pk_mul_f32 v[6:7], v[76:77], v[6:7]
	v_mov_b32_e32 v141, v140
	v_pk_fma_f32 v[4:5], v[74:75], v[8:9], v[4:5]
	v_pk_fma_f32 v[6:7], v[72:73], v[10:11], v[6:7]
	v_pk_mul_f32 v[0:1], v[0:1], v[140:141]
	v_pk_fma_f32 v[4:5], v[86:87], v[70:71], v[4:5]
	v_pk_fma_f32 v[6:7], v[84:85], v[68:69], v[6:7]
	v_pk_mul_f32 v[2:3], v[2:3], v[4:5]
	v_pk_mul_f32 v[0:1], v[0:1], v[6:7]
	s_andn2_b64 vcc, exec, s[6:7]
	v_cvt_pk_bf16_f32 v0, v0, v1
	v_cvt_pk_bf16_f32 v1, v2, v3
	v_lshlrev_b64 v[2:3], 11, v[114:115]
	v_lshl_add_u64 v[2:3], s[26:27], 0, v[2:3]
	v_lshl_add_u64 v[2:3], v[2:3], 0, v[12:13]
	s_mov_b64 s[6:7], -1
	global_store_dwordx2 v[2:3], v[0:1], off
	s_cbranch_vccnz .LBB0_576
	s_and_b64 vcc, exec, s[8:9]
	s_cbranch_vccnz .LBB0_575
	s_barrier
	s_branch .LBB0_575

; #define LAS __attribute__((address_space(3)))
; __device__ __forceinline__ int opq(int v) { asm volatile("" : "+v"(v)); return v; }
;     __device__ __forceinline__ void operator()(f32x4 (&acc)[2][2][4][2], const Unit& u, int wr, int wc, int fr, int fq) const {
;     ...
;         for (int n = 0; n < 2; ++n) {
;             const int lc = wc * 32 + 8 * fq + 4 * n + opq(0);
;             const f32x4 wg0 = *(const LAS f32x4*)(cwL + lc), wg1 = *(const LAS f32x4*)(cwL + 256 + lc), wg2 = *(const LAS f32x4*)(cwL + 512 + lc), bg = *(const LAS f32x4*)(cwL + 768 + lc);
;             const f32x4 wv0 = *(const LAS f32x4*)(cwL + 128 + lc), wv1 = *(const LAS f32x4*)(cwL + 384 + lc), wv2 = *(const LAS f32x4*)(cwL + 640 + lc), bv = *(const LAS f32x4*)(cwL + 896 + lc);
; #pragma unroll
;             for (int ai = 0; ai < 2; ++ai)
; #pragma unroll
;                 for (int m = 0; m < 4; ++m) {
;                     f32x4 gv[2];
; #pragma unroll
;                     for (int bj = 0; bj < 2; ++bj) {
;                         const f32x4 cur = acc[ai][bj][m][n]; f32x4 p1 = ror4(cur, 1), p2 = ror4(cur, 2);
;                         if (m > 0) { const f32x4 pv = acc[ai][bj][m - 1][n]; const f32x4 q1 = ror4(pv, 1), q2 = ror4(pv, 2);
; #pragma unroll
;                             for (int e = 0; e < 4; ++e) { p1[e] = (fr == 0) ? q1[e] : p1[e]; p2[e] = (fr < 2) ? q2[e] : p2[e]; } }
;                         else { f32x4 h14 = (f32x4){0.f, 0.f, 0.f, 0.f}, h15 = h14;
;                             if (!(wr == 0 && ai == 0)) { const int sai = (wr == 1) ? ai : 0, swr = (wr == 1) ? 0 : 1; const int ox = opq(0);
;                                 const LAS float* hp = hl + (((((sai * 2 + swr) * 4 + wc) * 2 + 0) * 2 + bj) * 32 + 8 * fq + 4 * n) + ox;
;                                 const float r14 = rsL[sai * 128 + swr * 64 + 62 + ox], r15 = rsL[sai * 128 + swr * 64 + 63 + ox];
;                                 h14 = *(const LAS f32x4*)hp * r14; h15 = *(const LAS f32x4*)(hp + 64) * r15; }
.LBB0_1042:
	s_or_b64 exec, exec, s[12:13]
	v_mov_b32_e32 v72, v161
	v_add_u32_e32 v179, s87, v226
	v_mov_b32_dpp v227, v156 row_ror:1 row_mask:0xf bank_mask:0xf
	v_add_u32_e32 v72, v72, v179
	v_lshl_add_u32 v72, v72, 2, 0
	v_add_u32_e32 v73, 0x22440, v72
	v_add_u32_e32 v74, 0x22840, v72
	ds_read_b128 v[96:99], v73
	ds_read_b128 v[88:91], v74
	v_add_u32_e32 v73, 0x22c40, v72
	v_add_u32_e32 v74, 0x23040, v72
	ds_read_b128 v[92:95], v73
	ds_read_b128 v[100:103], v74
	v_add_u32_e32 v73, 0x22640, v72
	v_add_u32_e32 v74, 0x22a40, v72
	ds_read_b128 v[80:83], v73
	ds_read_b128 v[76:79], v74
	v_add_u32_e32 v73, 0x22e40, v72
	v_add_u32_e32 v84, 0x23240, v72
	ds_read_b128 v[72:75], v73
	ds_read_b128 v[84:87], v84
	v_mov_b32_dpp v189, v157 row_ror:1 row_mask:0xf bank_mask:0xf
	v_mov_b32_dpp v184, v158 row_ror:1 row_mask:0xf bank_mask:0xf
	v_mov_b32_dpp v160, v159 row_ror:1 row_mask:0xf bank_mask:0xf
	v_mov_b32_dpp v231, v156 row_ror:2 row_mask:0xf bank_mask:0xf
	v_mov_b32_dpp v230, v157 row_ror:2 row_mask:0xf bank_mask:0xf
	v_mov_b32_dpp v229, v158 row_ror:2 row_mask:0xf bank_mask:0xf
	v_mov_b32_dpp v228, v159 row_ror:2 row_mask:0xf bank_mask:0xf
	v_cndmask_b32_e64 v166, 0, 1, s[4:5]
	v_mov_b32_e32 v190, 0
	v_cmp_ne_u32_e64 s[16:17], 1, v166
	s_andn2_b64 vcc, exec, s[4:5]
	v_mov_b32_e32 v194, 0
	v_mov_b32_e32 v195, 0
	v_mov_b32_e32 v192, 0
	v_mov_b32_e32 v193, 0
	v_mov_b32_e32 v198, 0
	v_mov_b32_e32 v199, 0
	v_mov_b32_e32 v196, 0
	v_mov_b32_e32 v197, 0
	s_cbranch_vccnz .LBB0_1044
	v_mov_b32_e32 v166, v161
	s_nop 0
	v_lshlrev_b32_e32 v166, 2, v166
	v_add3_u32 v191, s63, v225, v166
	v_add_u32_e32 v166, s64, v166
	ds_read2_b32 v[202:203], v166 offset0:62 offset1:63
	ds_read_b128 v[166:169], v191
	ds_read_b128 v[198:201], v191 offset:256
	s_waitcnt lgkmcnt(1)
	v_pk_mul_f32 v[192:193], v[168:169], v[202:203] op_sel_hi:[1,0]
	v_pk_mul_f32 v[194:195], v[166:167], v[202:203] op_sel_hi:[1,0]
	s_waitcnt lgkmcnt(0)
	v_pk_mul_f32 v[196:197], v[200:201], v[202:203] op_sel:[0,1]
	v_pk_mul_f32 v[198:199], v[198:199], v[202:203] op_sel:[0,1]
.LBB0_1044:
	v_mov_b32_dpp v235, v152 row_ror:1 row_mask:0xf bank_mask:0xf
	v_mov_b32_dpp v234, v153 row_ror:1 row_mask:0xf bank_mask:0xf
	v_mov_b32_dpp v233, v154 row_ror:1 row_mask:0xf bank_mask:0xf
	v_mov_b32_dpp v232, v155 row_ror:1 row_mask:0xf bank_mask:0xf
	v_mov_b32_dpp v239, v152 row_ror:2 row_mask:0xf bank_mask:0xf
	v_mov_b32_dpp v238, v153 row_ror:2 row_mask:0xf bank_mask:0xf
	v_mov_b32_dpp v237, v154 row_ror:2 row_mask:0xf bank_mask:0xf
	v_mov_b32_dpp v236, v155 row_ror:2 row_mask:0xf bank_mask:0xf
	s_and_b64 vcc, exec, s[16:17]
	v_mov_b32_e32 v191, 0
	v_mov_b32_e32 v200, 0
	v_mov_b32_e32 v201, 0
	v_mov_b32_e32 v204, 0
	v_mov_b32_e32 v205, 0
	v_mov_b32_e32 v202, 0
	v_mov_b32_e32 v203, 0
	s_cbranch_vccnz .LBB0_1046
	v_mov_b32_e32 v166, v161
	s_nop 0
	v_lshlrev_b32_e32 v166, 2, v166
	v_add3_u32 v190, s63, v225, v166
	v_add_u32_e32 v166, s64, v166
	ds_read2_b32 v[204:205], v166 offset0:62 offset1:63
	ds_read_b128 v[166:169], v190 offset:128
	ds_read_b128 v[240:243], v190 offset:384
	s_waitcnt lgkmcnt(1)
	v_pk_mul_f32 v[200:201], v[168:169], v[204:205] op_sel_hi:[1,0]
	v_pk_mul_f32 v[190:191], v[166:167], v[204:205] op_sel_hi:[1,0]
	s_waitcnt lgkmcnt(0)
	v_pk_mul_f32 v[202:203], v[242:243], v[204:205] op_sel:[0,1]
	v_pk_mul_f32 v[204:205], v[240:241], v[204:205] op_sel:[0,1]

;     __device__ __forceinline__ void operator()(f32x4 (&acc)[2][2][4][2], const Unit& u, int wr, int wc, int fr, int fq) const {
;     ...
;         EPI_FOR_ROWS() { const float rs = rsL[ai * 128 + wr * 64 + m * 16 + fr];
; #pragma unroll
;             for (int bj = 0; bj < 2; ++bj) { acc[ai][bj][m][0] *= rs; acc[ai][bj][m][1] *= rs; } }
;         if (wr == 1 && fr >= 14) {
; #pragma unroll
;             for (int bj = 0; bj < 2; ++bj)
; #pragma unroll
;                 for (int n = 0; n < 2; ++n) *(f32x4*)(tail + ((size_t)u.pm * 2 + (fr - 14)) * NUP + bj * DFF + colg0 + 4 * n) = acc[1][bj][3][n]; }
;         if (wr == 0 && fr < 2) {
; #pragma unroll
;             for (int bj = 0; bj < 2; ++bj)
; #pragma unroll
;                 for (int n = 0; n < 2; ++n) *(f32x4*)(head + ((size_t)u.pm * 2 + fr) * NUP + bj * DFF + colg0 + 4 * n) = acc[0][bj][0][n]; }
;         const bool seq0 = (u.pm & 15) == 0;
; #pragma unroll
;         for (int n = 0; n < 2; ++n) {
;             const int lc = wc * 32 + 8 * fq + 4 * n + opq(0);
;             const f32x4 wg0 = *(const LAS f32x4*)(cwL + lc), wg1 = *(const LAS f32x4*)(cwL + 256 + lc), wg2 = *(const LAS f32x4*)(cwL + 512 + lc), bg = *(const LAS f32x4*)(cwL + 768 + lc);
;             const f32x4 wv0 = *(const LAS f32x4*)(cwL + 128 + lc), wv1 = *(const LAS f32x4*)(cwL + 384 + lc), wv2 = *(const LAS f32x4*)(cwL + 640 + lc), bv = *(const LAS f32x4*)(cwL + 896 + lc);
; #pragma unroll
;             for (int ai = 0; ai < 2; ++ai)
; #pragma unroll
;                 for (int m = 0; m < 4; ++m) {
;                     f32x4 gv[2];
; #pragma unroll
;                     for (int bj = 0; bj < 2; ++bj) {
;                         const f32x4 cur = acc[ai][bj][m][n]; f32x4 p1 = ror4(cur, 1), p2 = ror4(cur, 2);
;                         if (m > 0) { const f32x4 pv = acc[ai][bj][m - 1][n]; const f32x4 q1 = ror4(pv, 1), q2 = ror4(pv, 2);
; #pragma unroll
;                             for (int e = 0; e < 4; ++e) { p1[e] = (fr == 0) ? q1[e] : p1[e]; p2[e] = (fr < 2) ? q2[e] : p2[e]; } }
;                         else { f32x4 h14 = (f32x4){0.f, 0.f, 0.f, 0.f}, h15 = h14;
;                             if (!(wr == 0 && ai == 0)) { const int sai = (wr == 1) ? ai : 0, swr = (wr == 1) ? 0 : 1; const int ox = opq(0);
;                                 const LAS float* hp = hl + (((((sai * 2 + swr) * 4 + wc) * 2 + 0) * 2 + bj) * 32 + 8 * fq + 4 * n) + ox;
.LBB0_1048:
	s_or_b64 exec, exec, s[84:85]
	v_mov_b32_e32 v166, v185
	v_pk_mul_f32 v[168:169], v[150:151], v[166:167] op_sel_hi:[1,0]
	v_pk_mul_f32 v[150:151], v[134:135], v[182:183] op_sel_hi:[1,0]
	v_pk_mul_f32 v[188:189], v[132:133], v[182:183] op_sel_hi:[1,0]
	v_mov_b32_e32 v132, v183
	v_pk_mul_f32 v[134:135], v[116:117], v[180:181] op_sel_hi:[1,0]
	v_mov_b32_e32 v116, v181
	v_pk_mul_f32 v[194:195], v[148:149], v[166:167] op_sel_hi:[1,0]
	v_pk_mul_f32 v[196:197], v[142:143], v[166:167] op_sel_hi:[1,0]
	v_pk_mul_f32 v[190:191], v[146:147], v[182:183] op_sel_hi:[1,0]
	v_pk_mul_f32 v[192:193], v[144:145], v[182:183] op_sel_hi:[1,0]
	v_pk_mul_f32 v[146:147], v[138:139], v[132:133] op_sel_hi:[1,0]
	v_pk_mul_f32 v[148:149], v[136:137], v[132:133] op_sel_hi:[1,0]
	v_pk_mul_f32 v[144:145], v[130:131], v[132:133] op_sel_hi:[1,0]
	v_pk_mul_f32 v[142:143], v[128:129], v[132:133] op_sel_hi:[1,0]
	v_pk_mul_f32 v[138:139], v[126:127], v[180:181] op_sel_hi:[1,0]
	v_pk_mul_f32 v[130:131], v[122:123], v[116:117] op_sel_hi:[1,0]
	v_pk_mul_f32 v[132:133], v[120:121], v[116:117] op_sel_hi:[1,0]
	v_pk_mul_f32 v[126:127], v[110:111], v[116:117] op_sel_hi:[1,0]
	v_pk_mul_f32 v[128:129], v[108:109], v[116:117] op_sel_hi:[1,0]
	v_pk_mul_f32 v[122:123], v[114:115], v[178:179] op_sel_hi:[1,0]
	v_pk_mul_f32 v[114:115], v[106:107], v[178:179] op_sel_hi:[1,0]
	v_pk_mul_f32 v[166:167], v[140:141], v[166:167] op_sel_hi:[1,0]
	v_pk_mul_f32 v[140:141], v[124:125], v[180:181] op_sel_hi:[1,0]
	v_pk_mul_f32 v[136:137], v[118:119], v[180:181] op_sel_hi:[1,0]
	v_pk_mul_f32 v[124:125], v[112:113], v[178:179] op_sel_hi:[1,0]
	v_pk_mul_f32 v[120:121], v[104:105], v[178:179] op_sel_hi:[1,0]
	v_mov_b32_dpp v201, v194 row_ror:2 row_mask:0xf bank_mask:0xf
	v_mov_b32_dpp v202, v195 row_ror:2 row_mask:0xf bank_mask:0xf
	v_mov_b32_dpp v184, v194 row_ror:1 row_mask:0xf bank_mask:0xf
	v_mov_b32_dpp v198, v195 row_ror:1 row_mask:0xf bank_mask:0xf
	v_mov_b32_dpp v108, v156 row_ror:1 row_mask:0xf bank_mask:0xf
	v_mov_b32_dpp v111, v157 row_ror:1 row_mask:0xf bank_mask:0xf
	v_mov_b32_dpp v156, v156 row_ror:2 row_mask:0xf bank_mask:0xf
	v_mov_b32_dpp v157, v157 row_ror:2 row_mask:0xf bank_mask:0xf
	v_cndmask_b32_e64 v106, v201, v156, s[10:11]
	v_cndmask_b32_e64 v107, v202, v157, s[10:11]
	v_mov_b32_dpp v203, v168 row_ror:2 row_mask:0xf bank_mask:0xf
	v_mov_b32_dpp v204, v169 row_ror:2 row_mask:0xf bank_mask:0xf
	v_cndmask_b32_e64 v110, v184, v108, s[12:13]
	v_cndmask_b32_e64 v111, v198, v111, s[12:13]
	v_pk_fma_f32 v[106:107], v[96:97], v[106:107], v[100:101]
	v_mov_b32_dpp v199, v168 row_ror:1 row_mask:0xf bank_mask:0xf
	v_mov_b32_dpp v200, v169 row_ror:1 row_mask:0xf bank_mask:0xf
	v_mov_b32_dpp v112, v158 row_ror:1 row_mask:0xf bank_mask:0xf
	v_mov_b32_dpp v109, v159 row_ror:1 row_mask:0xf bank_mask:0xf
	v_mov_b32_dpp v158, v158 row_ror:2 row_mask:0xf bank_mask:0xf
	v_mov_b32_dpp v159, v159 row_ror:2 row_mask:0xf bank_mask:0xf
	v_pk_fma_f32 v[106:107], v[88:89], v[110:111], v[106:107]
	v_cndmask_b32_e64 v105, v204, v159, s[10:11]
	v_cndmask_b32_e64 v104, v203, v158, s[10:11]
	v_pk_fma_f32 v[106:107], v[194:195], v[92:93], v[106:107]
	v_mov_b32_dpp v194, v196 row_ror:2 row_mask:0xf bank_mask:0xf
	v_mov_b32_dpp v195, v197 row_ror:2 row_mask:0xf bank_mask:0xf
	v_cndmask_b32_e64 v109, v200, v109, s[12:13]
	v_cndmask_b32_e64 v108, v199, v112, s[12:13]
	v_pk_fma_f32 v[104:105], v[98:99], v[104:105], v[102:103]
	v_mov_b32_dpp v156, v166 row_ror:1 row_mask:0xf bank_mask:0xf
	v_mov_b32_dpp v158, v196 row_ror:1 row_mask:0xf bank_mask:0xf
	v_mov_b32_dpp v159, v197 row_ror:1 row_mask:0xf bank_mask:0xf
	v_mov_b32_dpp v112, v152 row_ror:1 row_mask:0xf bank_mask:0xf
	v_mov_b32_dpp v118, v154 row_ror:1 row_mask:0xf bank_mask:0xf
	v_mov_b32_dpp v113, v155 row_ror:1 row_mask:0xf bank_mask:0xf
	v_mov_b32_dpp v154, v154 row_ror:2 row_mask:0xf bank_mask:0xf
	v_mov_b32_dpp v155, v155 row_ror:2 row_mask:0xf bank_mask:0xf
	v_pk_fma_f32 v[104:105], v[90:91], v[108:109], v[104:105]
	v_cndmask_b32_e64 v109, v195, v155, s[10:11]
	v_cndmask_b32_e64 v108, v194, v154, s[10:11]
	v_cndmask_b32_e64 v113, v159, v113, s[12:13]
	v_cndmask_b32_e64 v116, v156, v112, s[12:13]
	v_cndmask_b32_e64 v112, v158, v118, s[12:13]
	v_pk_fma_f32 v[108:109], v[82:83], v[108:109], v[86:87]
	v_pk_fma_f32 v[104:105], v[168:169], v[94:95], v[104:105]
	v_pk_fma_f32 v[108:109], v[78:79], v[112:113], v[108:109]
	v_mul_f32_e32 v112, 0xbfb8aa3b, v106
	v_exp_f32_e32 v112, v112
	v_mov_b32_dpp v168, v166 row_ror:2 row_mask:0xf bank_mask:0xf
	v_mov_b32_dpp v169, v167 row_ror:2 row_mask:0xf bank_mask:0xf
	v_mov_b32_dpp v157, v167 row_ror:1 row_mask:0xf bank_mask:0xf
	v_add_f32_e32 v112, 1.0, v112
	v_mov_b32_dpp v117, v153 row_ror:1 row_mask:0xf bank_mask:0xf
	v_mov_b32_dpp v152, v152 row_ror:2 row_mask:0xf bank_mask:0xf
	v_mov_b32_dpp v153, v153 row_ror:2 row_mask:0xf bank_mask:0xf
	v_rcp_f32_e32 v112, v112
	v_cndmask_b32_e64 v110, v168, v152, s[10:11]
	v_cndmask_b32_e64 v111, v169, v153, s[10:11]
	v_cndmask_b32_e64 v117, v157, v117, s[12:13]
	v_pk_fma_f32 v[110:111], v[80:81], v[110:111], v[84:85]
	v_mul_f32_e32 v106, v106, v112
	v_pk_fma_f32 v[110:111], v[76:77], v[116:117], v[110:111]
	v_pk_fma_f32 v[108:109], v[196:197], v[74:75], v[108:109]
	v_pk_fma_f32 v[110:111], v[166:167], v[72:73], v[110:111]
	v_mov_b64_e32 v[116:117], s[24:25]
	v_mul_f32_e32 v106, v106, v110
	v_mul_f32_e32 v110, 0xbfb8aa3b, v107
	v_exp_f32_e32 v110, v110
	v_lshlrev_b64 v[118:119], 1, v[186:187]
	v_add_f32_e32 v110, 1.0, v110
	v_rcp_f32_e32 v110, v110
	s_nop 0
	v_mul_f32_e32 v107, v107, v110
	v_mul_f32_e32 v110, 0xbfb8aa3b, v104
	v_exp_f32_e32 v110, v110
; #define LAS __attribute__((address_space(3)))
; __device__ __forceinline__ unsigned cvt_pk_bf16(float lo, float hi) { unsigned r; asm volatile("v_cvt_pk_bf16_f32 %0, %1, %2" : "=v"(r) : "v"(lo), "v"(hi)); return r; }
;     __device__ __forceinline__ void operator()(f32x4 (&acc)[2][2][4][2], const Unit& u, int wr, int wc, int fr, int fq) const {
;     ...
;                 for (int m = 0; m < 4; ++m) {
;                     f32x4 gv[2];
; #pragma unroll
;                     for (int bj = 0; bj < 2; ++bj) {
;                         const f32x4 cur = acc[ai][bj][m][n]; f32x4 p1 = ror4(cur, 1), p2 = ror4(cur, 2);
;                         if (m > 0) { const f32x4 pv = acc[ai][bj][m - 1][n]; const f32x4 q1 = ror4(pv, 1), q2 = ror4(pv, 2);
; #pragma unroll
;                             for (int e = 0; e < 4; ++e) { p1[e] = (fr == 0) ? q1[e] : p1[e]; p2[e] = (fr < 2) ? q2[e] : p2[e]; } }
;                         else { f32x4 h14 = (f32x4){0.f, 0.f, 0.f, 0.f}, h15 = h14;
;                             if (!(wr == 0 && ai == 0)) { const int sai = (wr == 1) ? ai : 0, swr = (wr == 1) ? 0 : 1; const int ox = opq(0);
;                                 const LAS float* hp = hl + (((((sai * 2 + swr) * 4 + wc) * 2 + 0) * 2 + bj) * 32 + 8 * fq + 4 * n) + ox;
;                                 const float r14 = rsL[sai * 128 + swr * 64 + 62 + ox], r15 = rsL[sai * 128 + swr * 64 + 63 + ox];
;                                 h14 = *(const LAS f32x4*)hp * r14; h15 = *(const LAS f32x4*)(hp + 64) * r15; }
; #pragma unroll
;                             for (int e = 0; e < 4; ++e) { p1[e] = (fr == 0) ? h15[e] : p1[e]; p2[e] = (fr == 0) ? h14[e] : ((fr == 1) ? h15[e] : p2[e]); } }
;                         const f32x4 w0 = bj ? wv0 : wg0, w1 = bj ? wv1 : wg1, w2 = bj ? wv2 : wg2, bb = bj ? bv : bg;
;                         gv[bj] = bb + w0 * p2 + w1 * p1 + w2 * cur;
;                     }
;                     float o[4];
; #pragma unroll
;                     for (int e = 0; e < 4; ++e) o[e] = gv[0][e] * sigm(gv[0][e]) * gv[1][e];
;                     u32x2 w; w.x = cvt_pk_bf16(o[0], o[1]); w.y = cvt_pk_bf16(o[2], o[3]);
;                     const bool edge = (wr == 0 && ai == 0 && m == 0 && fr < 2 && !seq0);
;                     if (!edge) *(u32x2*)(act + (size_t)(row0 + ai * 128 + m * 16) * DFF + colg0 + 4 * n) = w;
	v_mul_f32_e32 v107, v107, v111
	v_cvt_pk_bf16_f32 v106, v106, v107
	v_add_f32_e32 v110, 1.0, v110
	v_rcp_f32_e32 v110, v110
	s_nop 0
	v_mul_f32_e32 v104, v104, v110
	v_mul_f32_e32 v104, v104, v108
	v_mul_f32_e32 v108, 0xbfb8aa3b, v105
	v_exp_f32_e32 v108, v108
	s_nop 0
	v_add_f32_e32 v108, 1.0, v108
	v_rcp_f32_e32 v108, v108
	s_nop 0
	v_mul_f32_e32 v105, v105, v108
	v_mul_f32_e32 v105, v105, v109
	v_cvt_pk_bf16_f32 v107, v104, v105
	v_add_u32_e32 v104, 16, v160
	v_mad_i64_i32 v[104:105], s[68:69], v104, s46, v[116:117]
	v_lshl_add_u64 v[104:105], v[104:105], 0, v[118:119]
	global_store_dwordx2 v[104:105], v[106:107], off
	v_mov_b32_dpp v205, v192 row_ror:2 row_mask:0xf bank_mask:0xf
	v_mov_b32_dpp v227, v193 row_ror:2 row_mask:0xf bank_mask:0xf
	v_mov_b32_dpp v228, v190 row_ror:2 row_mask:0xf bank_mask:0xf
	v_mov_b32_dpp v229, v191 row_ror:2 row_mask:0xf bank_mask:0xf
	v_mov_b32_dpp v166, v192 row_ror:1 row_mask:0xf bank_mask:0xf
	v_mov_b32_dpp v167, v193 row_ror:1 row_mask:0xf bank_mask:0xf
	v_mov_b32_dpp v196, v190 row_ror:1 row_mask:0xf bank_mask:0xf
	v_mov_b32_dpp v197, v191 row_ror:1 row_mask:0xf bank_mask:0xf
	v_cndmask_b32_e64 v107, v229, v204, s[10:11]
	v_cndmask_b32_e64 v108, v205, v201, s[10:11]
	v_cndmask_b32_e64 v109, v227, v202, s[10:11]
	v_cndmask_b32_e64 v106, v228, v203, s[10:11]
	v_cndmask_b32_e64 v111, v197, v200, s[12:13]
	v_cndmask_b32_e64 v112, v166, v184, s[12:13]
	v_cndmask_b32_e64 v113, v167, v198, s[12:13]
	v_cndmask_b32_e64 v110, v196, v199, s[12:13]
	v_pk_fma_f32 v[106:107], v[98:99], v[106:107], v[102:103]
	v_pk_fma_f32 v[108:109], v[96:97], v[108:109], v[100:101]
	v_pk_fma_f32 v[106:107], v[90:91], v[110:111], v[106:107]
	v_pk_fma_f32 v[108:109], v[88:89], v[112:113], v[108:109]
	v_mov_b32_dpp v199, v150 row_ror:2 row_mask:0xf bank_mask:0xf
	v_mov_b32_dpp v200, v151 row_ror:2 row_mask:0xf bank_mask:0xf
	v_pk_fma_f32 v[106:107], v[190:191], v[94:95], v[106:107]
	v_pk_fma_f32 v[108:109], v[192:193], v[92:93], v[108:109]
	v_mov_b32_dpp v191, v150 row_ror:1 row_mask:0xf bank_mask:0xf
	v_mov_b32_dpp v192, v151 row_ror:1 row_mask:0xf bank_mask:0xf
	v_cndmask_b32_e64 v111, v200, v195, s[10:11]
	v_cndmask_b32_e64 v110, v199, v194, s[10:11]
	v_cndmask_b32_e64 v153, v192, v159, s[12:13]
	v_cndmask_b32_e64 v152, v191, v158, s[12:13]
	v_pk_fma_f32 v[110:111], v[82:83], v[110:111], v[86:87]
	v_mov_b32_dpp v193, v188 row_ror:2 row_mask:0xf bank_mask:0xf
	v_pk_fma_f32 v[110:111], v[78:79], v[152:153], v[110:111]
	v_mov_b32_dpp v198, v189 row_ror:2 row_mask:0xf bank_mask:0xf
	v_pk_fma_f32 v[110:111], v[150:151], v[74:75], v[110:111]
	v_mul_f32_e32 v150, 0xbfb8aa3b, v108
	v_exp_f32_e32 v150, v150
	v_mov_b32_dpp v184, v188 row_ror:1 row_mask:0xf bank_mask:0xf
	v_mov_b32_dpp v190, v189 row_ror:1 row_mask:0xf bank_mask:0xf
	v_add_f32_e32 v150, 1.0, v150
	v_rcp_f32_e32 v150, v150
	v_cndmask_b32_e64 v112, v193, v168, s[10:11]
	v_cndmask_b32_e64 v113, v198, v169, s[10:11]
	v_cndmask_b32_e64 v154, v184, v156, s[12:13]
	v_cndmask_b32_e64 v155, v190, v157, s[12:13]
	v_pk_fma_f32 v[112:113], v[80:81], v[112:113], v[84:85]
	v_mul_f32_e32 v108, v108, v150
	v_pk_fma_f32 v[112:113], v[76:77], v[154:155], v[112:113]
	s_nop 0
	v_pk_fma_f32 v[112:113], v[188:189], v[72:73], v[112:113]
	s_nop 0
	v_mul_f32_e32 v108, v108, v112
	v_mul_f32_e32 v112, 0xbfb8aa3b, v109
	v_exp_f32_e32 v112, v112
	s_nop 0
	v_add_f32_e32 v112, 1.0, v112
	v_rcp_f32_e32 v112, v112
	s_nop 0
	v_mul_f32_e32 v109, v109, v112
	v_mul_f32_e32 v112, 0xbfb8aa3b, v106
	v_exp_f32_e32 v112, v112
	v_mul_f32_e32 v109, v109, v113
	v_cvt_pk_bf16_f32 v108, v108, v109
	v_add_f32_e32 v112, 1.0, v112
	v_rcp_f32_e32 v112, v112
	s_nop 0
	v_mul_f32_e32 v106, v106, v112
	v_mul_f32_e32 v106, v106, v110
	v_mul_f32_e32 v110, 0xbfb8aa3b, v107
	v_exp_f32_e32 v110, v110
	s_nop 0
	v_add_f32_e32 v110, 1.0, v110
	v_rcp_f32_e32 v110, v110
	s_nop 0
	v_mul_f32_e32 v107, v107, v110
	v_mul_f32_e32 v107, v107, v111
	v_cvt_pk_bf16_f32 v109, v106, v107
	v_add_u32_e32 v106, 32, v160
	v_mad_i64_i32 v[106:107], s[68:69], v106, s46, v[116:117]
	v_lshl_add_u64 v[106:107], v[106:107], 0, v[118:119]
	global_store_dwordx2 v[106:107], v[108:109], off
	v_mov_b32_dpp v108, v148 row_ror:2 row_mask:0xf bank_mask:0xf
	v_mov_b32_dpp v111, v149 row_ror:2 row_mask:0xf bank_mask:0xf
	v_mov_b32_dpp v112, v148 row_ror:1 row_mask:0xf bank_mask:0xf
	v_mov_b32_dpp v151, v149 row_ror:1 row_mask:0xf bank_mask:0xf
	v_mov_b32_dpp v150, v146 row_ror:2 row_mask:0xf bank_mask:0xf
	v_mov_b32_dpp v109, v147 row_ror:2 row_mask:0xf bank_mask:0xf
	v_mov_b32_dpp v152, v146 row_ror:1 row_mask:0xf bank_mask:0xf
	v_mov_b32_dpp v113, v147 row_ror:1 row_mask:0xf bank_mask:0xf
	v_cndmask_b32_e64 v110, v108, v205, s[10:11]
	v_cndmask_b32_e64 v111, v111, v227, s[10:11]
	v_cndmask_b32_e64 v109, v109, v229, s[10:11]
	v_cndmask_b32_e64 v108, v150, v228, s[10:11]
	v_cndmask_b32_e64 v150, v112, v166, s[12:13]
	v_cndmask_b32_e64 v151, v151, v167, s[12:13]
	v_pk_fma_f32 v[110:111], v[96:97], v[110:111], v[100:101]
	v_cndmask_b32_e64 v113, v113, v197, s[12:13]
	v_cndmask_b32_e64 v112, v152, v196, s[12:13]
	v_pk_fma_f32 v[108:109], v[98:99], v[108:109], v[102:103]
	v_pk_fma_f32 v[110:111], v[88:89], v[150:151], v[110:111]
	v_pk_fma_f32 v[108:109], v[90:91], v[112:113], v[108:109]
	v_pk_fma_f32 v[110:111], v[148:149], v[92:93], v[110:111]
	v_mov_b32_dpp v148, v142 row_ror:1 row_mask:0xf bank_mask:0xf
	v_mov_b32_dpp v152, v144 row_ror:1 row_mask:0xf bank_mask:0xf
	v_mov_b32_dpp v112, v142 row_ror:2 row_mask:0xf bank_mask:0xf
	v_mov_b32_dpp v150, v144 row_ror:2 row_mask:0xf bank_mask:0xf
	v_pk_fma_f32 v[108:109], v[146:147], v[94:95], v[108:109]
; #define LAS __attribute__((address_space(3)))
; __device__ __forceinline__ unsigned cvt_pk_bf16(float lo, float hi) { unsigned r; asm volatile("v_cvt_pk_bf16_f32 %0, %1, %2" : "=v"(r) : "v"(lo), "v"(hi)); return r; }
;     __device__ __forceinline__ void operator()(f32x4 (&acc)[2][2][4][2], const Unit& u, int wr, int wc, int fr, int fq) const {
;     ...
;                 for (int m = 0; m < 4; ++m) {
;                     f32x4 gv[2];
; #pragma unroll
;                     for (int bj = 0; bj < 2; ++bj) {
;                         const f32x4 cur = acc[ai][bj][m][n]; f32x4 p1 = ror4(cur, 1), p2 = ror4(cur, 2);
;                         if (m > 0) { const f32x4 pv = acc[ai][bj][m - 1][n]; const f32x4 q1 = ror4(pv, 1), q2 = ror4(pv, 2);
; #pragma unroll
;                             for (int e = 0; e < 4; ++e) { p1[e] = (fr == 0) ? q1[e] : p1[e]; p2[e] = (fr < 2) ? q2[e] : p2[e]; } }
;                         else { f32x4 h14 = (f32x4){0.f, 0.f, 0.f, 0.f}, h15 = h14;
;                             if (!(wr == 0 && ai == 0)) { const int sai = (wr == 1) ? ai : 0, swr = (wr == 1) ? 0 : 1; const int ox = opq(0);
;                                 const LAS float* hp = hl + (((((sai * 2 + swr) * 4 + wc) * 2 + 0) * 2 + bj) * 32 + 8 * fq + 4 * n) + ox;
;                                 const float r14 = rsL[sai * 128 + swr * 64 + 62 + ox], r15 = rsL[sai * 128 + swr * 64 + 63 + ox];
;                                 h14 = *(const LAS f32x4*)hp * r14; h15 = *(const LAS f32x4*)(hp + 64) * r15; }
; #pragma unroll
;                             for (int e = 0; e < 4; ++e) { p1[e] = (fr == 0) ? h15[e] : p1[e]; p2[e] = (fr == 0) ? h14[e] : ((fr == 1) ? h15[e] : p2[e]); } }
;                         const f32x4 w0 = bj ? wv0 : wg0, w1 = bj ? wv1 : wg1, w2 = bj ? wv2 : wg2, bb = bj ? bv : bg;
;                         gv[bj] = bb + w0 * p2 + w1 * p1 + w2 * cur;
;                     }
;                     float o[4];
; #pragma unroll
;                     for (int e = 0; e < 4; ++e) o[e] = gv[0][e] * sigm(gv[0][e]) * gv[1][e];
;                     u32x2 w; w.x = cvt_pk_bf16(o[0], o[1]); w.y = cvt_pk_bf16(o[2], o[3]);
;                     const bool edge = (wr == 0 && ai == 0 && m == 0 && fr < 2 && !seq0);
;                     if (!edge) *(u32x2*)(act + (size_t)(row0 + ai * 128 + m * 16) * DFF + colg0 + 4 * n) = w;
	v_mov_b32_dpp v113, v145 row_ror:2 row_mask:0xf bank_mask:0xf
	v_cndmask_b32_e64 v146, v112, v193, s[10:11]
	v_cndmask_b32_e64 v112, v150, v199, s[10:11]
	v_cndmask_b32_e64 v150, v148, v184, s[12:13]
	v_cndmask_b32_e64 v148, v152, v191, s[12:13]
	v_mul_f32_e32 v152, 0xbfb8aa3b, v110
	v_mov_b32_dpp v149, v145 row_ror:1 row_mask:0xf bank_mask:0xf
	v_exp_f32_e32 v152, v152
	v_cndmask_b32_e64 v113, v113, v200, s[10:11]
	v_cndmask_b32_e64 v149, v149, v192, s[12:13]
	v_pk_fma_f32 v[112:113], v[82:83], v[112:113], v[86:87]
	v_mov_b32_dpp v147, v143 row_ror:2 row_mask:0xf bank_mask:0xf
	v_pk_fma_f32 v[112:113], v[78:79], v[148:149], v[112:113]
	v_mov_b32_dpp v151, v143 row_ror:1 row_mask:0xf bank_mask:0xf
	v_pk_fma_f32 v[112:113], v[144:145], v[74:75], v[112:113]
	v_add_f32_e32 v144, 1.0, v152
	v_rcp_f32_e32 v144, v144
	v_mul_f32_e32 v145, 0xbfb8aa3b, v111
	v_cndmask_b32_e64 v147, v147, v198, s[10:11]
	v_exp_f32_e32 v145, v145
	v_cndmask_b32_e64 v151, v151, v190, s[12:13]
	v_pk_fma_f32 v[146:147], v[80:81], v[146:147], v[84:85]
	v_mul_f32_e32 v110, v110, v144
	v_pk_fma_f32 v[146:147], v[76:77], v[150:151], v[146:147]
	v_mul_f32_e32 v144, 0xbfb8aa3b, v108
	v_pk_fma_f32 v[142:143], v[142:143], v[72:73], v[146:147]
	v_exp_f32_e32 v144, v144
	v_mul_f32_e32 v110, v110, v142
	v_add_f32_e32 v142, 1.0, v145
	v_rcp_f32_e32 v142, v142
	v_mul_f32_e32 v145, 0xbfb8aa3b, v109
	v_exp_f32_e32 v145, v145
	v_mul_f32_e32 v111, v111, v142
	v_add_f32_e32 v142, 1.0, v144
	v_rcp_f32_e32 v142, v142
	v_add_f32_e32 v144, 1.0, v145
	v_rcp_f32_e32 v144, v144
	v_mul_f32_e32 v111, v111, v143
	v_mul_f32_e32 v108, v108, v142
	v_mul_f32_e32 v108, v108, v112
	v_mul_f32_e32 v109, v109, v144
	v_mul_f32_e32 v109, v109, v113
	v_cvt_pk_bf16_f32 v110, v110, v111
	v_cvt_pk_bf16_f32 v111, v108, v109
	v_add_u32_e32 v108, 48, v160
	v_mad_i64_i32 v[108:109], s[68:69], v108, s46, v[116:117]
	v_lshl_add_u64 v[108:109], v[108:109], 0, v[118:119]
	global_store_dwordx2 v[108:109], v[110:111], off
	v_mov_b32_e32 v110, v161
	v_lshl_add_u32 v142, v226, 2, s65
	v_lshlrev_b32_e32 v110, 2, v110
	v_add_u32_e32 v144, v142, v110
	v_add_u32_e32 v110, s62, v110
	ds_read2_b32 v[148:149], v110 offset0:62 offset1:63
	ds_read_b128 v[110:113], v144
	ds_read_b128 v[144:147], v144 offset:256
	v_mov_b32_dpp v150, v140 row_ror:1 row_mask:0xf bank_mask:0xf
	v_mov_b32_dpp v154, v140 row_ror:2 row_mask:0xf bank_mask:0xf
	v_mov_b32_dpp v155, v141 row_ror:2 row_mask:0xf bank_mask:0xf
	s_waitcnt lgkmcnt(0)
	v_pk_mul_f32 v[144:145], v[144:145], v[148:149] op_sel:[0,1]
	v_pk_mul_f32 v[112:113], v[112:113], v[148:149] op_sel_hi:[1,0]
	v_pk_mul_f32 v[110:111], v[110:111], v[148:149] op_sel_hi:[1,0]
	v_pk_mul_f32 v[146:147], v[146:147], v[148:149] op_sel:[0,1]
	v_cndmask_b32_e64 v148, v150, v144, s[12:13]
	v_cndmask_b32_e64 v144, v154, v144, s[14:15]
	v_mov_b32_dpp v151, v141 row_ror:1 row_mask:0xf bank_mask:0xf
	v_cndmask_b32_e64 v110, v144, v110, s[12:13]
	v_cndmask_b32_e64 v144, v155, v145, s[14:15]
	v_mov_b32_dpp v152, v138 row_ror:1 row_mask:0xf bank_mask:0xf
	v_mov_b32_dpp v156, v138 row_ror:2 row_mask:0xf bank_mask:0xf
	v_mov_b32_dpp v157, v139 row_ror:2 row_mask:0xf bank_mask:0xf
	v_cndmask_b32_e64 v111, v144, v111, s[12:13]
	v_mov_b32_dpp v153, v139 row_ror:1 row_mask:0xf bank_mask:0xf
	v_cndmask_b32_e64 v149, v151, v145, s[12:13]
	v_pk_fma_f32 v[110:111], v[96:97], v[110:111], v[100:101]
	v_cndmask_b32_e64 v144, v152, v146, s[12:13]
	v_cndmask_b32_e64 v145, v156, v146, s[14:15]
	v_cndmask_b32_e64 v146, v157, v147, s[14:15]
	v_pk_fma_f32 v[110:111], v[88:89], v[148:149], v[110:111]
	v_cndmask_b32_e64 v112, v145, v112, s[12:13]
	v_cndmask_b32_e64 v145, v153, v147, s[12:13]
	v_cndmask_b32_e64 v113, v146, v113, s[12:13]
	v_pk_fma_f32 v[146:147], v[140:141], v[92:93], v[110:111]
	v_mov_b32_e32 v110, v161
	v_pk_fma_f32 v[112:113], v[98:99], v[112:113], v[102:103]
	v_mov_b32_dpp v158, v134 row_ror:1 row_mask:0xf bank_mask:0xf
	v_pk_fma_f32 v[112:113], v[90:91], v[144:145], v[112:113]
	v_lshlrev_b32_e32 v110, 2, v110
	v_pk_fma_f32 v[144:145], v[138:139], v[94:95], v[112:113]
	v_add_u32_e32 v138, v142, v110
	v_add_u32_e32 v110, s62, v110
	ds_read2_b32 v[148:149], v110 offset0:62 offset1:63
	ds_read_b128 v[110:113], v138 offset:128
	ds_read_b128 v[138:141], v138 offset:384
	v_mov_b32_dpp v168, v134 row_ror:2 row_mask:0xf bank_mask:0xf
	v_mov_b32_dpp v169, v135 row_ror:2 row_mask:0xf bank_mask:0xf
	s_waitcnt lgkmcnt(0)
; #define LAS __attribute__((address_space(3)))
; __device__ __forceinline__ unsigned cvt_pk_bf16(float lo, float hi) { unsigned r; asm volatile("v_cvt_pk_bf16_f32 %0, %1, %2" : "=v"(r) : "v"(lo), "v"(hi)); return r; }
;     __device__ __forceinline__ void operator()(f32x4 (&acc)[2][2][4][2], const Unit& u, int wr, int wc, int fr, int fq) const {
;     ...
;                 for (int m = 0; m < 4; ++m) {
;                     f32x4 gv[2];
; #pragma unroll
;                     for (int bj = 0; bj < 2; ++bj) {
;                         const f32x4 cur = acc[ai][bj][m][n]; f32x4 p1 = ror4(cur, 1), p2 = ror4(cur, 2);
;                         if (m > 0) { const f32x4 pv = acc[ai][bj][m - 1][n]; const f32x4 q1 = ror4(pv, 1), q2 = ror4(pv, 2);
; #pragma unroll
;                             for (int e = 0; e < 4; ++e) { p1[e] = (fr == 0) ? q1[e] : p1[e]; p2[e] = (fr < 2) ? q2[e] : p2[e]; } }
;                         else { f32x4 h14 = (f32x4){0.f, 0.f, 0.f, 0.f}, h15 = h14;
;                             if (!(wr == 0 && ai == 0)) { const int sai = (wr == 1) ? ai : 0, swr = (wr == 1) ? 0 : 1; const int ox = opq(0);
;                                 const LAS float* hp = hl + (((((sai * 2 + swr) * 4 + wc) * 2 + 0) * 2 + bj) * 32 + 8 * fq + 4 * n) + ox;
;                                 const float r14 = rsL[sai * 128 + swr * 64 + 62 + ox], r15 = rsL[sai * 128 + swr * 64 + 63 + ox];
;                                 h14 = *(const LAS f32x4*)hp * r14; h15 = *(const LAS f32x4*)(hp + 64) * r15; }
; #pragma unroll
;                             for (int e = 0; e < 4; ++e) { p1[e] = (fr == 0) ? h15[e] : p1[e]; p2[e] = (fr == 0) ? h14[e] : ((fr == 1) ? h15[e] : p2[e]); } }
;                         const f32x4 w0 = bj ? wv0 : wg0, w1 = bj ? wv1 : wg1, w2 = bj ? wv2 : wg2, bb = bj ? bv : bg;
;                         gv[bj] = bb + w0 * p2 + w1 * p1 + w2 * cur;
;                     }
;                     float o[4];
; #pragma unroll
;                     for (int e = 0; e < 4; ++e) o[e] = gv[0][e] * sigm(gv[0][e]) * gv[1][e];
;                     u32x2 w; w.x = cvt_pk_bf16(o[0], o[1]); w.y = cvt_pk_bf16(o[2], o[3]);
;                     const bool edge = (wr == 0 && ai == 0 && m == 0 && fr < 2 && !seq0);
;                     if (!edge) *(u32x2*)(act + (size_t)(row0 + ai * 128 + m * 16) * DFF + colg0 + 4 * n) = w;
	v_pk_mul_f32 v[138:139], v[138:139], v[148:149] op_sel:[0,1]
	v_mov_b32_dpp v159, v135 row_ror:1 row_mask:0xf bank_mask:0xf
	v_mov_b32_dpp v166, v136 row_ror:1 row_mask:0xf bank_mask:0xf
	v_mov_b32_dpp v184, v136 row_ror:2 row_mask:0xf bank_mask:0xf
	v_mov_b32_dpp v188, v137 row_ror:2 row_mask:0xf bank_mask:0xf
	v_pk_mul_f32 v[112:113], v[112:113], v[148:149] op_sel_hi:[1,0]
	v_pk_mul_f32 v[110:111], v[110:111], v[148:149] op_sel_hi:[1,0]
	v_pk_mul_f32 v[140:141], v[140:141], v[148:149] op_sel:[0,1]
	v_cndmask_b32_e64 v148, v158, v138, s[12:13]
	v_cndmask_b32_e64 v138, v168, v138, s[14:15]
	v_cndmask_b32_e64 v110, v138, v110, s[12:13]
	v_cndmask_b32_e64 v138, v169, v139, s[14:15]
	v_cndmask_b32_e64 v149, v159, v139, s[12:13]
	v_cndmask_b32_e64 v111, v138, v111, s[12:13]
	v_cndmask_b32_e64 v138, v166, v140, s[12:13]
	v_cndmask_b32_e64 v139, v184, v140, s[14:15]
	v_cndmask_b32_e64 v140, v188, v141, s[14:15]
	v_cndmask_b32_e64 v113, v140, v113, s[12:13]
	v_mul_f32_e32 v140, 0xbfb8aa3b, v146
	v_mov_b32_dpp v167, v137 row_ror:1 row_mask:0xf bank_mask:0xf
	v_exp_f32_e32 v140, v140
	v_cndmask_b32_e64 v112, v139, v112, s[12:13]
	v_cndmask_b32_e64 v139, v167, v141, s[12:13]
	v_pk_fma_f32 v[112:113], v[82:83], v[112:113], v[86:87]
	v_pk_fma_f32 v[110:111], v[80:81], v[110:111], v[84:85]
	v_pk_fma_f32 v[112:113], v[78:79], v[138:139], v[112:113]
	v_pk_fma_f32 v[110:111], v[76:77], v[148:149], v[110:111]
	v_pk_fma_f32 v[112:113], v[136:137], v[74:75], v[112:113]
	v_add_f32_e32 v136, 1.0, v140
	v_rcp_f32_e32 v136, v136
	v_mul_f32_e32 v137, 0xbfb8aa3b, v147
	v_exp_f32_e32 v137, v137
	v_pk_fma_f32 v[110:111], v[134:135], v[72:73], v[110:111]
	v_mul_f32_e32 v135, 0xbfb8aa3b, v144
	v_mul_f32_e32 v134, v146, v136
	v_exp_f32_e32 v135, v135
	v_mul_f32_e32 v136, 0xbfb8aa3b, v145
	v_exp_f32_e32 v136, v136
	v_mul_f32_e32 v110, v134, v110
	v_add_f32_e32 v134, 1.0, v137
	v_rcp_f32_e32 v134, v134
	v_add_f32_e32 v135, 1.0, v135
	v_rcp_f32_e32 v135, v135
	v_add_f32_e32 v136, 1.0, v136
	v_rcp_f32_e32 v136, v136
	v_mul_f32_e32 v134, v147, v134
	v_mul_f32_e32 v111, v134, v111
	v_mul_f32_e32 v134, v144, v135
	v_add_u32_e32 v143, 0x80, v160
	v_mul_f32_e32 v134, v134, v112
	v_mul_f32_e32 v112, v145, v136
	v_mul_f32_e32 v113, v112, v113
	v_cvt_pk_bf16_f32 v112, v110, v111
	v_mad_i64_i32 v[110:111], s[68:69], v143, s46, v[116:117]
	v_lshl_add_u64 v[110:111], v[110:111], 0, v[118:119]
	v_cvt_pk_bf16_f32 v113, v134, v113
	global_store_dwordx2 v[110:111], v[112:113], off
	v_mov_b32_dpp v145, v132 row_ror:2 row_mask:0xf bank_mask:0xf
	v_mov_b32_dpp v146, v133 row_ror:2 row_mask:0xf bank_mask:0xf
	v_mov_b32_dpp v147, v130 row_ror:2 row_mask:0xf bank_mask:0xf
	v_mov_b32_dpp v148, v131 row_ror:2 row_mask:0xf bank_mask:0xf
	v_mov_b32_dpp v140, v132 row_ror:1 row_mask:0xf bank_mask:0xf
	v_mov_b32_dpp v141, v133 row_ror:1 row_mask:0xf bank_mask:0xf
	v_mov_b32_dpp v143, v130 row_ror:1 row_mask:0xf bank_mask:0xf
	v_mov_b32_dpp v144, v131 row_ror:1 row_mask:0xf bank_mask:0xf
	v_cndmask_b32_e64 v113, v148, v157, s[10:11]
	v_cndmask_b32_e64 v134, v145, v154, s[10:11]
	v_cndmask_b32_e64 v135, v146, v155, s[10:11]
	v_cndmask_b32_e64 v112, v147, v156, s[10:11]
	v_cndmask_b32_e64 v137, v144, v153, s[12:13]
	v_cndmask_b32_e64 v138, v140, v150, s[12:13]
	v_cndmask_b32_e64 v139, v141, v151, s[12:13]
	v_cndmask_b32_e64 v136, v143, v152, s[12:13]
	v_pk_fma_f32 v[112:113], v[98:99], v[112:113], v[102:103]
	v_pk_fma_f32 v[134:135], v[96:97], v[134:135], v[100:101]
	v_mov_b32_dpp v155, v126 row_ror:2 row_mask:0xf bank_mask:0xf
	v_mov_b32_dpp v156, v127 row_ror:2 row_mask:0xf bank_mask:0xf
	v_pk_fma_f32 v[112:113], v[90:91], v[136:137], v[112:113]
	v_pk_fma_f32 v[134:135], v[88:89], v[138:139], v[134:135]
	v_mov_b32_dpp v151, v126 row_ror:1 row_mask:0xf bank_mask:0xf
	v_mov_b32_dpp v152, v127 row_ror:1 row_mask:0xf bank_mask:0xf
	v_pk_fma_f32 v[112:113], v[130:131], v[94:95], v[112:113]
	v_pk_fma_f32 v[130:131], v[132:133], v[92:93], v[134:135]
	v_cndmask_b32_e64 v133, v156, v188, s[10:11]
	v_cndmask_b32_e64 v132, v155, v184, s[10:11]
	v_cndmask_b32_e64 v137, v152, v167, s[12:13]
	v_cndmask_b32_e64 v136, v151, v166, s[12:13]
	v_pk_fma_f32 v[132:133], v[82:83], v[132:133], v[86:87]
	v_mov_b32_dpp v153, v128 row_ror:2 row_mask:0xf bank_mask:0xf
	v_pk_fma_f32 v[132:133], v[78:79], v[136:137], v[132:133]
	v_mov_b32_dpp v154, v129 row_ror:2 row_mask:0xf bank_mask:0xf
	v_pk_fma_f32 v[126:127], v[126:127], v[74:75], v[132:133]
	v_mul_f32_e32 v132, 0xbfb8aa3b, v130
	v_exp_f32_e32 v132, v132
	v_mov_b32_dpp v149, v128 row_ror:1 row_mask:0xf bank_mask:0xf
	v_mov_b32_dpp v150, v129 row_ror:1 row_mask:0xf bank_mask:0xf
	v_add_f32_e32 v132, 1.0, v132
	v_rcp_f32_e32 v132, v132
	v_cndmask_b32_e64 v134, v153, v168, s[10:11]
	v_cndmask_b32_e64 v135, v154, v169, s[10:11]
	v_cndmask_b32_e64 v138, v149, v158, s[12:13]
	v_cndmask_b32_e64 v139, v150, v159, s[12:13]
	v_pk_fma_f32 v[134:135], v[80:81], v[134:135], v[84:85]
	v_mul_f32_e32 v130, v130, v132
	v_pk_fma_f32 v[134:135], v[76:77], v[138:139], v[134:135]
	s_nop 0
	v_pk_fma_f32 v[128:129], v[128:129], v[72:73], v[134:135]
	s_nop 0
	v_mul_f32_e32 v128, v130, v128
	v_mul_f32_e32 v130, 0xbfb8aa3b, v131
	v_exp_f32_e32 v130, v130
	s_nop 0
	v_add_f32_e32 v130, 1.0, v130
	v_rcp_f32_e32 v130, v130
	s_nop 0
	v_mul_f32_e32 v130, v131, v130
	v_mul_f32_e32 v129, v130, v129
	v_mul_f32_e32 v130, 0xbfb8aa3b, v112
	v_exp_f32_e32 v130, v130
	s_nop 0
	v_add_f32_e32 v130, 1.0, v130
	v_rcp_f32_e32 v130, v130
	s_nop 0
	v_mul_f32_e32 v112, v112, v130
	v_mul_f32_e32 v112, v112, v126
	v_mul_f32_e32 v126, 0xbfb8aa3b, v113
	v_exp_f32_e32 v126, v126
	s_nop 0
	v_add_f32_e32 v126, 1.0, v126
; #define LAS __attribute__((address_space(3)))
; __device__ __forceinline__ unsigned cvt_pk_bf16(float lo, float hi) { unsigned r; asm volatile("v_cvt_pk_bf16_f32 %0, %1, %2" : "=v"(r) : "v"(lo), "v"(hi)); return r; }
;     __device__ __forceinline__ void operator()(f32x4 (&acc)[2][2][4][2], const Unit& u, int wr, int wc, int fr, int fq) const {
;     ...
;                 for (int m = 0; m < 4; ++m) {
;                     f32x4 gv[2];
; #pragma unroll
;                     for (int bj = 0; bj < 2; ++bj) {
;                         const f32x4 cur = acc[ai][bj][m][n]; f32x4 p1 = ror4(cur, 1), p2 = ror4(cur, 2);
;                         if (m > 0) { const f32x4 pv = acc[ai][bj][m - 1][n]; const f32x4 q1 = ror4(pv, 1), q2 = ror4(pv, 2);
; #pragma unroll
;                             for (int e = 0; e < 4; ++e) { p1[e] = (fr == 0) ? q1[e] : p1[e]; p2[e] = (fr < 2) ? q2[e] : p2[e]; } }
;                         else { f32x4 h14 = (f32x4){0.f, 0.f, 0.f, 0.f}, h15 = h14;
;                             if (!(wr == 0 && ai == 0)) { const int sai = (wr == 1) ? ai : 0, swr = (wr == 1) ? 0 : 1; const int ox = opq(0);
;                                 const LAS float* hp = hl + (((((sai * 2 + swr) * 4 + wc) * 2 + 0) * 2 + bj) * 32 + 8 * fq + 4 * n) + ox;
;                                 const float r14 = rsL[sai * 128 + swr * 64 + 62 + ox], r15 = rsL[sai * 128 + swr * 64 + 63 + ox];
;                                 h14 = *(const LAS f32x4*)hp * r14; h15 = *(const LAS f32x4*)(hp + 64) * r15; }
; #pragma unroll
;                             for (int e = 0; e < 4; ++e) { p1[e] = (fr == 0) ? h15[e] : p1[e]; p2[e] = (fr == 0) ? h14[e] : ((fr == 1) ? h15[e] : p2[e]); } }
;                         const f32x4 w0 = bj ? wv0 : wg0, w1 = bj ? wv1 : wg1, w2 = bj ? wv2 : wg2, bb = bj ? bv : bg;
;                         gv[bj] = bb + w0 * p2 + w1 * p1 + w2 * cur;
;                     }
;                     float o[4];
; #pragma unroll
;                     for (int e = 0; e < 4; ++e) o[e] = gv[0][e] * sigm(gv[0][e]) * gv[1][e];
;                     u32x2 w; w.x = cvt_pk_bf16(o[0], o[1]); w.y = cvt_pk_bf16(o[2], o[3]);
;                     const bool edge = (wr == 0 && ai == 0 && m == 0 && fr < 2 && !seq0);
;                     if (!edge) *(u32x2*)(act + (size_t)(row0 + ai * 128 + m * 16) * DFF + colg0 + 4 * n) = w;
	v_rcp_f32_e32 v126, v126
	s_nop 0
	v_mul_f32_e32 v113, v113, v126
	v_mul_f32_e32 v113, v113, v127
	v_cvt_pk_bf16_f32 v126, v128, v129
	v_cvt_pk_bf16_f32 v127, v112, v113
	v_add_u32_e32 v112, 0x90, v160
	v_mad_i64_i32 v[112:113], s[68:69], v112, s46, v[116:117]
	v_lshl_add_u64 v[112:113], v[112:113], 0, v[118:119]
	global_store_dwordx2 v[112:113], v[126:127], off
	v_mov_b32_dpp v157, v122 row_ror:2 row_mask:0xf bank_mask:0xf
	v_mov_b32_dpp v158, v123 row_ror:2 row_mask:0xf bank_mask:0xf
	v_mov_b32_dpp v136, v122 row_ror:1 row_mask:0xf bank_mask:0xf
	v_mov_b32_dpp v137, v123 row_ror:1 row_mask:0xf bank_mask:0xf
	v_mov_b32_dpp v138, v124 row_ror:2 row_mask:0xf bank_mask:0xf
	v_mov_b32_dpp v139, v125 row_ror:2 row_mask:0xf bank_mask:0xf
	v_cndmask_b32_e64 v127, v158, v148, s[10:11]
	v_cndmask_b32_e64 v126, v157, v147, s[10:11]
	v_mov_b32_dpp v134, v124 row_ror:1 row_mask:0xf bank_mask:0xf
	v_mov_b32_dpp v135, v125 row_ror:1 row_mask:0xf bank_mask:0xf
	v_cndmask_b32_e64 v131, v137, v144, s[12:13]
	v_cndmask_b32_e64 v130, v136, v143, s[12:13]
	v_pk_fma_f32 v[126:127], v[98:99], v[126:127], v[102:103]
	v_mov_b32_dpp v147, v114 row_ror:2 row_mask:0xf bank_mask:0xf
	v_mov_b32_dpp v148, v115 row_ror:2 row_mask:0xf bank_mask:0xf
	v_cndmask_b32_e64 v128, v138, v145, s[10:11]
	v_cndmask_b32_e64 v129, v139, v146, s[10:11]
	v_pk_fma_f32 v[126:127], v[90:91], v[130:131], v[126:127]
	v_mov_b32_dpp v143, v114 row_ror:1 row_mask:0xf bank_mask:0xf
	v_mov_b32_dpp v144, v115 row_ror:1 row_mask:0xf bank_mask:0xf
	v_cndmask_b32_e64 v132, v134, v140, s[12:13]
	v_cndmask_b32_e64 v133, v135, v141, s[12:13]
	v_pk_fma_f32 v[128:129], v[96:97], v[128:129], v[100:101]
	v_pk_fma_f32 v[122:123], v[122:123], v[94:95], v[126:127]
	v_cndmask_b32_e64 v127, v148, v156, s[10:11]
	v_cndmask_b32_e64 v126, v147, v155, s[10:11]
	v_pk_fma_f32 v[128:129], v[88:89], v[132:133], v[128:129]
	v_cndmask_b32_e64 v131, v144, v152, s[12:13]
	v_cndmask_b32_e64 v130, v143, v151, s[12:13]
	v_pk_fma_f32 v[126:127], v[82:83], v[126:127], v[86:87]
	v_pk_fma_f32 v[124:125], v[124:125], v[92:93], v[128:129]
	v_pk_fma_f32 v[126:127], v[78:79], v[130:131], v[126:127]
	v_mov_b32_dpp v145, v120 row_ror:2 row_mask:0xf bank_mask:0xf
	v_pk_fma_f32 v[114:115], v[114:115], v[74:75], v[126:127]
	v_mul_f32_e32 v126, 0xbfb8aa3b, v124
	v_exp_f32_e32 v126, v126
	v_mov_b32_dpp v146, v121 row_ror:2 row_mask:0xf bank_mask:0xf
	v_mov_b32_dpp v140, v120 row_ror:1 row_mask:0xf bank_mask:0xf
	v_mov_b32_dpp v141, v121 row_ror:1 row_mask:0xf bank_mask:0xf
	v_add_f32_e32 v126, 1.0, v126
	v_rcp_f32_e32 v126, v126
	v_cndmask_b32_e64 v128, v145, v153, s[10:11]
	v_cndmask_b32_e64 v129, v146, v154, s[10:11]
	v_cndmask_b32_e64 v132, v140, v149, s[12:13]
	v_cndmask_b32_e64 v133, v141, v150, s[12:13]
	v_pk_fma_f32 v[128:129], v[80:81], v[128:129], v[84:85]
	v_mul_f32_e32 v124, v124, v126
	v_pk_fma_f32 v[128:129], v[76:77], v[132:133], v[128:129]
	s_nop 0
	v_pk_fma_f32 v[120:121], v[120:121], v[72:73], v[128:129]
	s_nop 0
	v_mul_f32_e32 v120, v124, v120
	v_mul_f32_e32 v124, 0xbfb8aa3b, v125
	v_exp_f32_e32 v124, v124
	s_nop 0
	v_add_f32_e32 v124, 1.0, v124
	v_rcp_f32_e32 v124, v124
	s_nop 0
	v_mul_f32_e32 v124, v125, v124
	v_mul_f32_e32 v121, v124, v121
	v_mul_f32_e32 v124, 0xbfb8aa3b, v122
	v_exp_f32_e32 v124, v124
	v_cvt_pk_bf16_f32 v120, v120, v121
	s_nop 0
	v_add_f32_e32 v124, 1.0, v124
	v_rcp_f32_e32 v124, v124
	s_nop 0
	v_mul_f32_e32 v122, v122, v124
	v_mul_f32_e32 v114, v122, v114
	v_mul_f32_e32 v122, 0xbfb8aa3b, v123
	v_exp_f32_e32 v122, v122
	s_nop 0
	v_add_f32_e32 v122, 1.0, v122
	v_rcp_f32_e32 v122, v122
	s_nop 0
	v_mul_f32_e32 v122, v123, v122
	v_mul_f32_e32 v115, v122, v115
	v_cvt_pk_bf16_f32 v121, v114, v115
	v_add_u32_e32 v114, 0xa0, v160
	v_mad_i64_i32 v[114:115], s[68:69], v114, s46, v[116:117]
	v_lshl_add_u64 v[114:115], v[114:115], 0, v[118:119]
	global_store_dwordx2 v[114:115], v[120:121], off
	v_mov_b32_dpp v120, v68 row_ror:2 row_mask:0xf bank_mask:0xf
	v_mov_b32_dpp v123, v69 row_ror:2 row_mask:0xf bank_mask:0xf
	v_mov_b32_dpp v126, v70 row_ror:2 row_mask:0xf bank_mask:0xf
	v_mov_b32_dpp v121, v71 row_ror:2 row_mask:0xf bank_mask:0xf
	v_mov_b32_dpp v124, v68 row_ror:1 row_mask:0xf bank_mask:0xf
	v_mov_b32_dpp v127, v69 row_ror:1 row_mask:0xf bank_mask:0xf
	v_mov_b32_dpp v128, v70 row_ror:1 row_mask:0xf bank_mask:0xf
	v_mov_b32_dpp v125, v71 row_ror:1 row_mask:0xf bank_mask:0xf
	v_cndmask_b32_e64 v121, v121, v158, s[10:11]
	v_cndmask_b32_e64 v122, v120, v138, s[10:11]
	v_cndmask_b32_e64 v123, v123, v139, s[10:11]
	v_cndmask_b32_e64 v120, v126, v157, s[10:11]
	v_cndmask_b32_e64 v125, v125, v137, s[12:13]
	v_cndmask_b32_e64 v126, v124, v134, s[12:13]
	v_cndmask_b32_e64 v127, v127, v135, s[12:13]
	v_cndmask_b32_e64 v124, v128, v136, s[12:13]
	v_pk_fma_f32 v[98:99], v[98:99], v[120:121], v[102:103]
	v_pk_fma_f32 v[96:97], v[96:97], v[122:123], v[100:101]
	v_pk_fma_f32 v[90:91], v[90:91], v[124:125], v[98:99]
	v_pk_fma_f32 v[88:89], v[88:89], v[126:127], v[96:97]
	v_pk_fma_f32 v[70:71], v[70:71], v[94:95], v[90:91]
	v_pk_fma_f32 v[68:69], v[68:69], v[92:93], v[88:89]
	v_mov_b32_dpp v88, v64 row_ror:2 row_mask:0xf bank_mask:0xf
	v_mov_b32_dpp v91, v65 row_ror:2 row_mask:0xf bank_mask:0xf
; #define LAS __attribute__((address_space(3)))
; __device__ __forceinline__ int opq(int v) { asm volatile("" : "+v"(v)); return v; }
;     __device__ __forceinline__ void operator()(f32x4 (&acc)[2][2][4][2], const Unit& u, int wr, int wc, int fr, int fq) const {
;     ...
;         for (int n = 0; n < 2; ++n) {
;             const int lc = wc * 32 + 8 * fq + 4 * n + opq(0);
;             const f32x4 wg0 = *(const LAS f32x4*)(cwL + lc), wg1 = *(const LAS f32x4*)(cwL + 256 + lc), wg2 = *(const LAS f32x4*)(cwL + 512 + lc), bg = *(const LAS f32x4*)(cwL + 768 + lc);
;             const f32x4 wv0 = *(const LAS f32x4*)(cwL + 128 + lc), wv1 = *(const LAS f32x4*)(cwL + 384 + lc), wv2 = *(const LAS f32x4*)(cwL + 640 + lc), bv = *(const LAS f32x4*)(cwL + 896 + lc);
; #pragma unroll
;             for (int ai = 0; ai < 2; ++ai)
; #pragma unroll
;                 for (int m = 0; m < 4; ++m) {
;                     f32x4 gv[2];
; #pragma unroll
;                     for (int bj = 0; bj < 2; ++bj) {
;                         const f32x4 cur = acc[ai][bj][m][n]; f32x4 p1 = ror4(cur, 1), p2 = ror4(cur, 2);
;                         if (m > 0) { const f32x4 pv = acc[ai][bj][m - 1][n]; const f32x4 q1 = ror4(pv, 1), q2 = ror4(pv, 2);
; #pragma unroll
;                             for (int e = 0; e < 4; ++e) { p1[e] = (fr == 0) ? q1[e] : p1[e]; p2[e] = (fr < 2) ? q2[e] : p2[e]; } }
;                         else { f32x4 h14 = (f32x4){0.f, 0.f, 0.f, 0.f}, h15 = h14;
;                             if (!(wr == 0 && ai == 0)) { const int sai = (wr == 1) ? ai : 0, swr = (wr == 1) ? 0 : 1; const int ox = opq(0);
;                                 const LAS float* hp = hl + (((((sai * 2 + swr) * 4 + wc) * 2 + 0) * 2 + bj) * 32 + 8 * fq + 4 * n) + ox;
;                                 const float r14 = rsL[sai * 128 + swr * 64 + 62 + ox], r15 = rsL[sai * 128 + swr * 64 + 63 + ox];
;                                 h14 = *(const LAS f32x4*)hp * r14; h15 = *(const LAS f32x4*)(hp + 64) * r15; }
	v_mov_b32_dpp v94, v66 row_ror:2 row_mask:0xf bank_mask:0xf
	v_cndmask_b32_e64 v90, v88, v145, s[10:11]
	v_cndmask_b32_e64 v91, v91, v146, s[10:11]
	v_mov_b32_dpp v89, v67 row_ror:2 row_mask:0xf bank_mask:0xf
	v_pk_fma_f32 v[80:81], v[80:81], v[90:91], v[84:85]
	v_mul_f32_e32 v84, 0xbfb8aa3b, v68
	v_mov_b32_dpp v92, v64 row_ror:1 row_mask:0xf bank_mask:0xf
	v_mov_b32_dpp v96, v66 row_ror:1 row_mask:0xf bank_mask:0xf
	v_mov_b32_dpp v93, v67 row_ror:1 row_mask:0xf bank_mask:0xf
	v_exp_f32_e32 v84, v84
	v_cndmask_b32_e64 v89, v89, v148, s[10:11]
	v_cndmask_b32_e64 v88, v94, v147, s[10:11]
	v_cndmask_b32_e64 v93, v93, v144, s[12:13]
	v_cndmask_b32_e64 v94, v92, v140, s[12:13]
	v_cndmask_b32_e64 v92, v96, v143, s[12:13]
	v_pk_fma_f32 v[82:83], v[82:83], v[88:89], v[86:87]
	v_mov_b32_dpp v95, v65 row_ror:1 row_mask:0xf bank_mask:0xf
	v_pk_fma_f32 v[78:79], v[78:79], v[92:93], v[82:83]
	s_nop 0
	v_pk_fma_f32 v[66:67], v[66:67], v[74:75], v[78:79]
	v_add_f32_e32 v74, 1.0, v84
	v_rcp_f32_e32 v74, v74
	v_mul_f32_e32 v75, 0xbfb8aa3b, v69
	v_exp_f32_e32 v75, v75
	v_cndmask_b32_e64 v95, v95, v141, s[12:13]
	v_pk_fma_f32 v[76:77], v[76:77], v[94:95], v[80:81]
	v_mul_f32_e32 v68, v68, v74
	v_pk_fma_f32 v[64:65], v[64:65], v[72:73], v[76:77]
	v_mul_f32_e32 v72, 0xbfb8aa3b, v70
	v_mul_f32_e32 v64, v68, v64
	v_add_f32_e32 v68, 1.0, v75
	v_rcp_f32_e32 v68, v68
	v_exp_f32_e32 v72, v72
	v_mul_f32_e32 v73, 0xbfb8aa3b, v71
	v_exp_f32_e32 v73, v73
	v_mul_f32_e32 v68, v69, v68
	v_add_f32_e32 v69, 1.0, v72
	v_rcp_f32_e32 v69, v69
	v_add_f32_e32 v72, 1.0, v73
	v_rcp_f32_e32 v72, v72
	v_mul_f32_e32 v65, v68, v65
	v_mul_f32_e32 v68, v70, v69
	v_mul_f32_e32 v66, v68, v66
	v_mul_f32_e32 v68, v71, v72
	v_mul_f32_e32 v67, v68, v67
	v_cvt_pk_bf16_f32 v64, v64, v65
	v_cvt_pk_bf16_f32 v65, v66, v67
	v_add_u32_e32 v66, 0xb0, v160
	v_mad_i64_i32 v[66:67], s[68:69], v66, s46, v[116:117]
	v_lshl_add_u64 v[96:97], v[66:67], 0, v[118:119]
	global_store_dwordx2 v[96:97], v[64:65], off
	v_mov_b32_e32 v64, v161
	v_mov_b32_dpp v129, v60 row_ror:1 row_mask:0xf bank_mask:0xf
	v_add_u32_e32 v64, v64, v179
	v_lshl_add_u32 v64, v64, 2, 0
	v_add_u32_e32 v65, 0x22450, v64
	v_add_u32_e32 v66, 0x22850, v64
	ds_read_b128 v[88:91], v65
	ds_read_b128 v[80:83], v66
	v_add_u32_e32 v65, 0x22c50, v64
	v_add_u32_e32 v66, 0x23050, v64
	ds_read_b128 v[84:87], v65
	ds_read_b128 v[92:95], v66
	v_add_u32_e32 v65, 0x22650, v64
	v_add_u32_e32 v66, 0x22a50, v64
	ds_read_b128 v[72:75], v65
	ds_read_b128 v[68:71], v66
	v_add_u32_e32 v65, 0x22e50, v64
	v_add_u32_e32 v76, 0x23250, v64
	ds_read_b128 v[64:67], v65
	ds_read_b128 v[76:79], v76
	v_mov_b32_dpp v128, v61 row_ror:1 row_mask:0xf bank_mask:0xf
	v_mov_b32_dpp v127, v62 row_ror:1 row_mask:0xf bank_mask:0xf
	v_mov_b32_dpp v126, v63 row_ror:1 row_mask:0xf bank_mask:0xf
	v_mov_b32_dpp v133, v60 row_ror:2 row_mask:0xf bank_mask:0xf
	v_mov_b32_dpp v132, v61 row_ror:2 row_mask:0xf bank_mask:0xf
	v_mov_b32_dpp v131, v62 row_ror:2 row_mask:0xf bank_mask:0xf
	v_mov_b32_dpp v130, v63 row_ror:2 row_mask:0xf bank_mask:0xf
	v_mov_b32_e32 v98, 0
	s_and_b64 vcc, exec, s[16:17]
	v_mov_b32_e32 v102, 0
	v_mov_b32_e32 v103, 0
	v_mov_b32_e32 v100, 0
	v_mov_b32_e32 v101, 0
	v_mov_b32_e32 v118, 0
	v_mov_b32_e32 v119, 0
	v_mov_b32_e32 v116, 0
	v_mov_b32_e32 v117, 0
	s_cbranch_vccnz .LBB0_1050
	v_mov_b32_e32 v99, v161
	s_nop 0
	v_lshlrev_b32_e32 v99, 2, v99
	v_add3_u32 v100, s63, v225, v99
	v_add_u32_e32 v99, s64, v99
	ds_read2_b32 v[124:125], v99 offset0:62 offset1:63
	ds_read_b128 v[116:119], v100 offset:16
	ds_read_b128 v[120:123], v100 offset:272
	s_waitcnt lgkmcnt(1)
	v_pk_mul_f32 v[100:101], v[118:119], v[124:125] op_sel_hi:[1,0]
	v_pk_mul_f32 v[102:103], v[116:117], v[124:125] op_sel_hi:[1,0]
	s_waitcnt lgkmcnt(0)
	v_pk_mul_f32 v[116:117], v[122:123], v[124:125] op_sel:[0,1]
	v_pk_mul_f32 v[118:119], v[120:121], v[124:125] op_sel:[0,1]
.LBB0_1050:
	v_mov_b32_dpp v137, v56 row_ror:1 row_mask:0xf bank_mask:0xf
	v_mov_b32_dpp v136, v57 row_ror:1 row_mask:0xf bank_mask:0xf
	v_mov_b32_dpp v135, v58 row_ror:1 row_mask:0xf bank_mask:0xf
	v_mov_b32_dpp v134, v59 row_ror:1 row_mask:0xf bank_mask:0xf
	v_mov_b32_dpp v141, v56 row_ror:2 row_mask:0xf bank_mask:0xf
	v_mov_b32_dpp v140, v57 row_ror:2 row_mask:0xf bank_mask:0xf
	v_mov_b32_dpp v139, v58 row_ror:2 row_mask:0xf bank_mask:0xf
	v_mov_b32_dpp v138, v59 row_ror:2 row_mask:0xf bank_mask:0xf
	s_and_b64 vcc, exec, s[16:17]
	v_mov_b32_e32 v99, 0
	v_mov_b32_e32 v120, 0
	v_mov_b32_e32 v121, 0
	v_mov_b32_e32 v124, 0
	v_mov_b32_e32 v125, 0
	v_mov_b32_e32 v122, 0
	v_mov_b32_e32 v123, 0
	s_cbranch_vccnz .LBB0_1052
	v_mov_b32_e32 v98, v161
	s_nop 0
	v_lshlrev_b32_e32 v98, 2, v98
	v_add3_u32 v99, s63, v225, v98
	v_add_u32_e32 v98, s64, v98
	ds_read2_b32 v[148:149], v98 offset0:62 offset1:63
	ds_read_b128 v[122:125], v99 offset:144
	ds_read_b128 v[144:147], v99 offset:400
	s_waitcnt lgkmcnt(1)
	v_pk_mul_f32 v[120:121], v[124:125], v[148:149] op_sel_hi:[1,0]
	v_pk_mul_f32 v[98:99], v[122:123], v[148:149] op_sel_hi:[1,0]
	s_waitcnt lgkmcnt(0)
	v_pk_mul_f32 v[122:123], v[146:147], v[148:149] op_sel:[0,1]
	v_pk_mul_f32 v[124:125], v[144:145], v[148:149] op_sel:[0,1]

; #define LAS __attribute__((address_space(3)))
; __device__ __forceinline__ unsigned cvt_pk_bf16(float lo, float hi) { unsigned r; asm volatile("v_cvt_pk_bf16_f32 %0, %1, %2" : "=v"(r) : "v"(lo), "v"(hi)); return r; }
;     __device__ __forceinline__ void operator()(f32x4 (&acc)[2][2][4][2], const Unit& u, int wr, int wc, int fr, int fq) const {
;     ...
;                 for (int m = 0; m < 4; ++m) {
;                     f32x4 gv[2];
; #pragma unroll
;                     for (int bj = 0; bj < 2; ++bj) {
;                         const f32x4 cur = acc[ai][bj][m][n]; f32x4 p1 = ror4(cur, 1), p2 = ror4(cur, 2);
;                         if (m > 0) { const f32x4 pv = acc[ai][bj][m - 1][n]; const f32x4 q1 = ror4(pv, 1), q2 = ror4(pv, 2);
; #pragma unroll
;                             for (int e = 0; e < 4; ++e) { p1[e] = (fr == 0) ? q1[e] : p1[e]; p2[e] = (fr < 2) ? q2[e] : p2[e]; } }
;                         else { f32x4 h14 = (f32x4){0.f, 0.f, 0.f, 0.f}, h15 = h14;
;                             if (!(wr == 0 && ai == 0)) { const int sai = (wr == 1) ? ai : 0, swr = (wr == 1) ? 0 : 1; const int ox = opq(0);
;                                 const LAS float* hp = hl + (((((sai * 2 + swr) * 4 + wc) * 2 + 0) * 2 + bj) * 32 + 8 * fq + 4 * n) + ox;
;                                 const float r14 = rsL[sai * 128 + swr * 64 + 62 + ox], r15 = rsL[sai * 128 + swr * 64 + 63 + ox];
;                                 h14 = *(const LAS f32x4*)hp * r14; h15 = *(const LAS f32x4*)(hp + 64) * r15; }
; #pragma unroll
;                             for (int e = 0; e < 4; ++e) { p1[e] = (fr == 0) ? h15[e] : p1[e]; p2[e] = (fr == 0) ? h14[e] : ((fr == 1) ? h15[e] : p2[e]); } }
;                         const f32x4 w0 = bj ? wv0 : wg0, w1 = bj ? wv1 : wg1, w2 = bj ? wv2 : wg2, bb = bj ? bv : bg;
;                         gv[bj] = bb + w0 * p2 + w1 * p1 + w2 * cur;
;                     }
;                     float o[4];
; #pragma unroll
;                     for (int e = 0; e < 4; ++e) o[e] = gv[0][e] * sigm(gv[0][e]) * gv[1][e];
;                     u32x2 w; w.x = cvt_pk_bf16(o[0], o[1]); w.y = cvt_pk_bf16(o[2], o[3]);
;                     const bool edge = (wr == 0 && ai == 0 && m == 0 && fr < 2 && !seq0);
;                     if (!edge) *(u32x2*)(act + (size_t)(row0 + ai * 128 + m * 16) * DFF + colg0 + 4 * n) = w;
.LBB0_1054:
	s_or_b64 exec, exec, s[16:17]
	v_mov_b32_e32 v98, v182
	v_mov_b32_e32 v99, v182
	v_mov_b32_e32 v118, v185
	v_mov_b32_e32 v119, v185
	v_mov_b32_e32 v184, v185
	v_mov_b32_e32 v100, v183
	v_mov_b32_e32 v101, v183
	v_pk_mul_f32 v[54:55], v[54:55], v[118:119]
	v_pk_mul_f32 v[118:119], v[46:47], v[118:119]
	v_pk_mul_f32 v[48:49], v[48:49], v[98:99]
	v_pk_mul_f32 v[46:47], v[36:37], v[98:99]
	v_mov_b32_e32 v98, v180
	v_mov_b32_e32 v99, v180
	v_mov_b32_e32 v102, v180
	v_mov_b32_e32 v103, v180
	v_mov_b32_e32 v116, v181
	v_mov_b32_e32 v117, v181
	v_mov_b32_e32 v179, v178
	v_pk_mul_f32 v[120:121], v[44:45], v[184:185]
	v_mov_b32_e32 v44, v182
	v_mov_b32_e32 v45, v182
	v_mov_b32_e32 v182, v183
	v_pk_mul_f32 v[36:37], v[32:33], v[100:101]
	v_pk_mul_f32 v[32:33], v[30:31], v[98:99]
	v_pk_mul_f32 v[30:31], v[22:23], v[98:99]
	v_mov_b32_e32 v180, v181
	v_mov_b32_e32 v98, v178
	v_mov_b32_e32 v99, v178
	v_pk_mul_f32 v[52:53], v[52:53], v[184:185]
	v_pk_mul_f32 v[50:51], v[50:51], v[44:45]
	v_pk_mul_f32 v[44:45], v[38:39], v[44:45]
	v_pk_mul_f32 v[42:43], v[42:43], v[182:183]
	v_pk_mul_f32 v[40:41], v[40:41], v[100:101]
	v_pk_mul_f32 v[38:39], v[34:35], v[182:183]
	v_pk_mul_f32 v[34:35], v[28:29], v[102:103]
	v_pk_mul_f32 v[28:29], v[20:21], v[102:103]
	v_pk_mul_f32 v[26:27], v[26:27], v[180:181]
	v_pk_mul_f32 v[24:25], v[24:25], v[116:117]
	v_pk_mul_f32 v[20:21], v[14:15], v[180:181]
	v_pk_mul_f32 v[22:23], v[12:13], v[116:117]
	v_pk_mul_f32 v[12:13], v[18:19], v[98:99]
	v_pk_mul_f32 v[14:15], v[16:17], v[178:179]
	v_pk_mul_f32 v[10:11], v[10:11], v[98:99]
	v_pk_mul_f32 v[8:9], v[8:9], v[178:179]
	v_mov_b32_dpp v102, v52 row_ror:2 row_mask:0xf bank_mask:0xf
	v_mov_b32_dpp v103, v53 row_ror:2 row_mask:0xf bank_mask:0xf
	v_mov_b32_dpp v98, v52 row_ror:1 row_mask:0xf bank_mask:0xf
	v_mov_b32_dpp v99, v53 row_ror:1 row_mask:0xf bank_mask:0xf
	v_mov_b32_dpp v100, v54 row_ror:1 row_mask:0xf bank_mask:0xf
	v_mov_b32_dpp v101, v55 row_ror:1 row_mask:0xf bank_mask:0xf
	v_mov_b32_dpp v116, v54 row_ror:2 row_mask:0xf bank_mask:0xf
	v_mov_b32_dpp v117, v55 row_ror:2 row_mask:0xf bank_mask:0xf
	v_mov_b32_dpp v122, v60 row_ror:1 row_mask:0xf bank_mask:0xf
	v_mov_b32_dpp v123, v61 row_ror:1 row_mask:0xf bank_mask:0xf
	v_mov_b32_dpp v124, v62 row_ror:1 row_mask:0xf bank_mask:0xf
	v_mov_b32_dpp v125, v63 row_ror:1 row_mask:0xf bank_mask:0xf
	v_mov_b32_dpp v60, v60 row_ror:2 row_mask:0xf bank_mask:0xf
	v_mov_b32_dpp v61, v61 row_ror:2 row_mask:0xf bank_mask:0xf
	v_mov_b32_dpp v62, v62 row_ror:2 row_mask:0xf bank_mask:0xf
	v_mov_b32_dpp v63, v63 row_ror:2 row_mask:0xf bank_mask:0xf
	v_cndmask_b32_e64 v18, v102, v60, s[10:11]
	v_cndmask_b32_e64 v19, v103, v61, s[10:11]
	v_cndmask_b32_e64 v17, v117, v63, s[10:11]
	v_cndmask_b32_e64 v16, v116, v62, s[10:11]
	v_cndmask_b32_e64 v61, v101, v125, s[12:13]
	v_cndmask_b32_e64 v62, v98, v122, s[12:13]
	v_cndmask_b32_e64 v63, v99, v123, s[12:13]
	v_cndmask_b32_e64 v60, v100, v124, s[12:13]
	v_pk_fma_f32 v[18:19], v[88:89], v[18:19], v[92:93]
	v_mov_b32_dpp v124, v118 row_ror:2 row_mask:0xf bank_mask:0xf
	v_mov_b32_dpp v125, v119 row_ror:2 row_mask:0xf bank_mask:0xf
	v_pk_fma_f32 v[16:17], v[90:91], v[16:17], v[94:95]
	v_pk_fma_f32 v[18:19], v[80:81], v[62:63], v[18:19]
	v_mov_b32_dpp v62, v118 row_ror:1 row_mask:0xf bank_mask:0xf
	v_mov_b32_dpp v63, v119 row_ror:1 row_mask:0xf bank_mask:0xf
	v_mov_b32_dpp v122, v120 row_ror:2 row_mask:0xf bank_mask:0xf
	v_mov_b32_dpp v123, v121 row_ror:2 row_mask:0xf bank_mask:0xf
	v_mov_b32_dpp v128, v58 row_ror:1 row_mask:0xf bank_mask:0xf
	v_mov_b32_dpp v129, v59 row_ror:1 row_mask:0xf bank_mask:0xf
	v_mov_b32_dpp v58, v58 row_ror:2 row_mask:0xf bank_mask:0xf
	v_mov_b32_dpp v59, v59 row_ror:2 row_mask:0xf bank_mask:0xf
	v_pk_fma_f32 v[16:17], v[82:83], v[60:61], v[16:17]
	v_pk_fma_f32 v[18:19], v[52:53], v[84:85], v[18:19]
	v_mov_b32_dpp v126, v56 row_ror:1 row_mask:0xf bank_mask:0xf
	v_mov_b32_dpp v127, v57 row_ror:1 row_mask:0xf bank_mask:0xf
	v_mov_b32_dpp v56, v56 row_ror:2 row_mask:0xf bank_mask:0xf
	v_mov_b32_dpp v57, v57 row_ror:2 row_mask:0xf bank_mask:0xf
	v_cndmask_b32_e64 v53, v125, v59, s[10:11]
	v_cndmask_b32_e64 v52, v124, v58, s[10:11]
	v_pk_fma_f32 v[16:17], v[54:55], v[86:87], v[16:17]
	v_cndmask_b32_e64 v54, v122, v56, s[10:11]
	v_cndmask_b32_e64 v55, v123, v57, s[10:11]
	v_cndmask_b32_e64 v57, v63, v129, s[12:13]
	v_cndmask_b32_e64 v56, v62, v128, s[12:13]
	v_pk_fma_f32 v[52:53], v[74:75], v[52:53], v[78:79]
	v_mov_b32_dpp v60, v120 row_ror:1 row_mask:0xf bank_mask:0xf
	v_pk_fma_f32 v[52:53], v[70:71], v[56:57], v[52:53]
	v_mul_f32_e32 v56, 0xbfb8aa3b, v18
	v_exp_f32_e32 v56, v56
	v_mov_b32_dpp v61, v121 row_ror:1 row_mask:0xf bank_mask:0xf
	v_add_f32_e32 v56, 1.0, v56
	v_rcp_f32_e32 v56, v56
	v_cndmask_b32_e64 v58, v60, v126, s[12:13]
	v_cndmask_b32_e64 v59, v61, v127, s[12:13]
	v_pk_fma_f32 v[54:55], v[72:73], v[54:55], v[76:77]
	v_mul_f32_e32 v18, v18, v56
	v_pk_fma_f32 v[54:55], v[68:69], v[58:59], v[54:55]
	v_pk_fma_f32 v[52:53], v[118:119], v[66:67], v[52:53]
	v_pk_fma_f32 v[54:55], v[120:121], v[64:65], v[54:55]
	s_nop 0
	v_mul_f32_e32 v18, v18, v54
	v_mul_f32_e32 v54, 0xbfb8aa3b, v19
	v_exp_f32_e32 v54, v54
	s_nop 0
	v_add_f32_e32 v54, 1.0, v54
	v_rcp_f32_e32 v54, v54
	s_nop 0
	v_mul_f32_e32 v19, v19, v54
	v_mul_f32_e32 v54, 0xbfb8aa3b, v16
	v_exp_f32_e32 v54, v54
	v_mul_f32_e32 v19, v19, v55
	v_add_f32_e32 v54, 1.0, v54
	v_rcp_f32_e32 v54, v54
	s_nop 0
	v_mul_f32_e32 v16, v16, v54
	v_mul_f32_e32 v52, v16, v52
	v_mul_f32_e32 v16, 0xbfb8aa3b, v17
	v_exp_f32_e32 v16, v16
	s_nop 0
	v_add_f32_e32 v16, 1.0, v16
	v_rcp_f32_e32 v16, v16
	s_nop 0
	v_mul_f32_e32 v16, v17, v16
; #define LAS __attribute__((address_space(3)))
; __device__ __forceinline__ unsigned cvt_pk_bf16(float lo, float hi) { unsigned r; asm volatile("v_cvt_pk_bf16_f32 %0, %1, %2" : "=v"(r) : "v"(lo), "v"(hi)); return r; }
;     __device__ __forceinline__ void operator()(f32x4 (&acc)[2][2][4][2], const Unit& u, int wr, int wc, int fr, int fq) const {
;     ...
;                 for (int m = 0; m < 4; ++m) {
;                     f32x4 gv[2];
; #pragma unroll
;                     for (int bj = 0; bj < 2; ++bj) {
;                         const f32x4 cur = acc[ai][bj][m][n]; f32x4 p1 = ror4(cur, 1), p2 = ror4(cur, 2);
;                         if (m > 0) { const f32x4 pv = acc[ai][bj][m - 1][n]; const f32x4 q1 = ror4(pv, 1), q2 = ror4(pv, 2);
; #pragma unroll
;                             for (int e = 0; e < 4; ++e) { p1[e] = (fr == 0) ? q1[e] : p1[e]; p2[e] = (fr < 2) ? q2[e] : p2[e]; } }
;                         else { f32x4 h14 = (f32x4){0.f, 0.f, 0.f, 0.f}, h15 = h14;
;                             if (!(wr == 0 && ai == 0)) { const int sai = (wr == 1) ? ai : 0, swr = (wr == 1) ? 0 : 1; const int ox = opq(0);
;                                 const LAS float* hp = hl + (((((sai * 2 + swr) * 4 + wc) * 2 + 0) * 2 + bj) * 32 + 8 * fq + 4 * n) + ox;
;                                 const float r14 = rsL[sai * 128 + swr * 64 + 62 + ox], r15 = rsL[sai * 128 + swr * 64 + 63 + ox];
;                                 h14 = *(const LAS f32x4*)hp * r14; h15 = *(const LAS f32x4*)(hp + 64) * r15; }
; #pragma unroll
;                             for (int e = 0; e < 4; ++e) { p1[e] = (fr == 0) ? h15[e] : p1[e]; p2[e] = (fr == 0) ? h14[e] : ((fr == 1) ? h15[e] : p2[e]); } }
;                         const f32x4 w0 = bj ? wv0 : wg0, w1 = bj ? wv1 : wg1, w2 = bj ? wv2 : wg2, bb = bj ? bv : bg;
;                         gv[bj] = bb + w0 * p2 + w1 * p1 + w2 * cur;
;                     }
;                     float o[4];
; #pragma unroll
;                     for (int e = 0; e < 4; ++e) o[e] = gv[0][e] * sigm(gv[0][e]) * gv[1][e];
;                     u32x2 w; w.x = cvt_pk_bf16(o[0], o[1]); w.y = cvt_pk_bf16(o[2], o[3]);
;                     const bool edge = (wr == 0 && ai == 0 && m == 0 && fr < 2 && !seq0);
;                     if (!edge) *(u32x2*)(act + (size_t)(row0 + ai * 128 + m * 16) * DFF + colg0 + 4 * n) = w;
	v_mul_f32_e32 v17, v16, v53
	v_cvt_pk_bf16_f32 v16, v18, v19
	v_cvt_pk_bf16_f32 v17, v52, v17
	global_store_dwordx2 v[104:105], v[16:17], off offset:8
	v_mov_b32_dpp v104, v48 row_ror:2 row_mask:0xf bank_mask:0xf
	v_mov_b32_dpp v105, v49 row_ror:2 row_mask:0xf bank_mask:0xf
	v_mov_b32_dpp v56, v48 row_ror:1 row_mask:0xf bank_mask:0xf
	v_mov_b32_dpp v57, v49 row_ror:1 row_mask:0xf bank_mask:0xf
	v_mov_b32_dpp v118, v50 row_ror:2 row_mask:0xf bank_mask:0xf
	v_mov_b32_dpp v119, v51 row_ror:2 row_mask:0xf bank_mask:0xf
	v_mov_b32_dpp v58, v50 row_ror:1 row_mask:0xf bank_mask:0xf
	v_mov_b32_dpp v59, v51 row_ror:1 row_mask:0xf bank_mask:0xf
	v_cndmask_b32_e64 v18, v104, v102, s[10:11]
	v_cndmask_b32_e64 v19, v105, v103, s[10:11]
	v_cndmask_b32_e64 v17, v119, v117, s[10:11]
	v_cndmask_b32_e64 v16, v118, v116, s[10:11]
	v_cndmask_b32_e64 v54, v56, v98, s[12:13]
	v_cndmask_b32_e64 v55, v57, v99, s[12:13]
	v_pk_fma_f32 v[18:19], v[88:89], v[18:19], v[92:93]
	v_mov_b32_dpp v116, v44 row_ror:2 row_mask:0xf bank_mask:0xf
	v_mov_b32_dpp v117, v45 row_ror:2 row_mask:0xf bank_mask:0xf
	v_cndmask_b32_e64 v53, v59, v101, s[12:13]
	v_cndmask_b32_e64 v52, v58, v100, s[12:13]
	v_pk_fma_f32 v[18:19], v[80:81], v[54:55], v[18:19]
	v_mov_b32_dpp v100, v44 row_ror:1 row_mask:0xf bank_mask:0xf
	v_mov_b32_dpp v101, v45 row_ror:1 row_mask:0xf bank_mask:0xf
	v_pk_fma_f32 v[16:17], v[90:91], v[16:17], v[94:95]
	v_pk_fma_f32 v[18:19], v[48:49], v[84:85], v[18:19]
	v_cndmask_b32_e64 v49, v117, v125, s[10:11]
	v_cndmask_b32_e64 v48, v116, v124, s[10:11]
	v_pk_fma_f32 v[16:17], v[82:83], v[52:53], v[16:17]
	v_cndmask_b32_e64 v53, v101, v63, s[12:13]
	v_cndmask_b32_e64 v52, v100, v62, s[12:13]
	v_pk_fma_f32 v[48:49], v[74:75], v[48:49], v[78:79]
	v_mov_b32_dpp v102, v46 row_ror:2 row_mask:0xf bank_mask:0xf
	v_pk_fma_f32 v[48:49], v[70:71], v[52:53], v[48:49]
	v_mov_b32_dpp v103, v47 row_ror:2 row_mask:0xf bank_mask:0xf
	v_pk_fma_f32 v[44:45], v[44:45], v[66:67], v[48:49]
	v_mul_f32_e32 v48, 0xbfb8aa3b, v18
	v_exp_f32_e32 v48, v48
	v_mov_b32_dpp v98, v46 row_ror:1 row_mask:0xf bank_mask:0xf
	v_mov_b32_dpp v99, v47 row_ror:1 row_mask:0xf bank_mask:0xf
	v_add_f32_e32 v48, 1.0, v48
	v_rcp_f32_e32 v48, v48
	v_pk_fma_f32 v[16:17], v[50:51], v[86:87], v[16:17]
	v_cndmask_b32_e64 v50, v102, v122, s[10:11]
	v_cndmask_b32_e64 v51, v103, v123, s[10:11]
	v_cndmask_b32_e64 v54, v98, v60, s[12:13]
	v_cndmask_b32_e64 v55, v99, v61, s[12:13]
	v_pk_fma_f32 v[50:51], v[72:73], v[50:51], v[76:77]
	v_mul_f32_e32 v18, v18, v48
	v_pk_fma_f32 v[50:51], v[68:69], v[54:55], v[50:51]
	s_nop 0
	v_pk_fma_f32 v[46:47], v[46:47], v[64:65], v[50:51]
	s_nop 0
	v_mul_f32_e32 v18, v18, v46
	v_mul_f32_e32 v46, 0xbfb8aa3b, v19
	v_exp_f32_e32 v46, v46
	s_nop 0
	v_add_f32_e32 v46, 1.0, v46
	v_rcp_f32_e32 v46, v46
	s_nop 0
	v_mul_f32_e32 v19, v19, v46
	v_mul_f32_e32 v46, 0xbfb8aa3b, v16
	v_exp_f32_e32 v46, v46
	v_mul_f32_e32 v19, v19, v47
	v_add_f32_e32 v46, 1.0, v46
	v_rcp_f32_e32 v46, v46
	s_nop 0
	v_mul_f32_e32 v16, v16, v46
	v_mul_f32_e32 v44, v16, v44
	v_mul_f32_e32 v16, 0xbfb8aa3b, v17
	v_exp_f32_e32 v16, v16
	s_nop 0
	v_add_f32_e32 v16, 1.0, v16
	v_rcp_f32_e32 v16, v16
	s_nop 0
	v_mul_f32_e32 v16, v17, v16
	v_mul_f32_e32 v17, v16, v45
	v_cvt_pk_bf16_f32 v16, v18, v19
	v_cvt_pk_bf16_f32 v17, v44, v17
	global_store_dwordx2 v[106:107], v[16:17], off offset:8
	v_mov_b32_dpp v16, v40 row_ror:2 row_mask:0xf bank_mask:0xf
	v_mov_b32_dpp v19, v41 row_ror:2 row_mask:0xf bank_mask:0xf
	v_mov_b32_dpp v44, v40 row_ror:1 row_mask:0xf bank_mask:0xf
	v_mov_b32_dpp v47, v41 row_ror:1 row_mask:0xf bank_mask:0xf
	v_mov_b32_dpp v46, v42 row_ror:2 row_mask:0xf bank_mask:0xf
	v_mov_b32_dpp v17, v43 row_ror:2 row_mask:0xf bank_mask:0xf
	v_mov_b32_dpp v48, v42 row_ror:1 row_mask:0xf bank_mask:0xf
	v_mov_b32_dpp v45, v43 row_ror:1 row_mask:0xf bank_mask:0xf
	v_cndmask_b32_e64 v18, v16, v104, s[10:11]
	v_cndmask_b32_e64 v19, v19, v105, s[10:11]
	v_cndmask_b32_e64 v17, v17, v119, s[10:11]
	v_cndmask_b32_e64 v16, v46, v118, s[10:11]
	v_cndmask_b32_e64 v46, v44, v56, s[12:13]
	v_cndmask_b32_e64 v47, v47, v57, s[12:13]
	v_pk_fma_f32 v[18:19], v[88:89], v[18:19], v[92:93]
	v_cndmask_b32_e64 v45, v45, v59, s[12:13]
	v_cndmask_b32_e64 v44, v48, v58, s[12:13]
	v_pk_fma_f32 v[16:17], v[90:91], v[16:17], v[94:95]
	v_pk_fma_f32 v[18:19], v[80:81], v[46:47], v[18:19]
	v_pk_fma_f32 v[16:17], v[82:83], v[44:45], v[16:17]
	v_pk_fma_f32 v[18:19], v[40:41], v[84:85], v[18:19]
	v_mov_b32_dpp v44, v36 row_ror:1 row_mask:0xf bank_mask:0xf
	v_mov_b32_dpp v48, v38 row_ror:1 row_mask:0xf bank_mask:0xf
	v_mov_b32_dpp v40, v36 row_ror:2 row_mask:0xf bank_mask:0xf
	v_mov_b32_dpp v46, v38 row_ror:2 row_mask:0xf bank_mask:0xf
	v_pk_fma_f32 v[16:17], v[42:43], v[86:87], v[16:17]
	v_mov_b32_dpp v41, v39 row_ror:2 row_mask:0xf bank_mask:0xf
	v_cndmask_b32_e64 v42, v40, v102, s[10:11]
	v_cndmask_b32_e64 v40, v46, v116, s[10:11]
	v_cndmask_b32_e64 v46, v44, v98, s[12:13]
	v_cndmask_b32_e64 v44, v48, v100, s[12:13]
	v_mul_f32_e32 v48, 0xbfb8aa3b, v18
	v_mov_b32_dpp v45, v39 row_ror:1 row_mask:0xf bank_mask:0xf
	v_exp_f32_e32 v48, v48
	v_cndmask_b32_e64 v41, v41, v117, s[10:11]
	v_cndmask_b32_e64 v45, v45, v101, s[12:13]
	v_pk_fma_f32 v[40:41], v[74:75], v[40:41], v[78:79]
	v_mov_b32_dpp v43, v37 row_ror:2 row_mask:0xf bank_mask:0xf
	v_pk_fma_f32 v[40:41], v[70:71], v[44:45], v[40:41]
	v_mov_b32_dpp v47, v37 row_ror:1 row_mask:0xf bank_mask:0xf
	v_pk_fma_f32 v[38:39], v[38:39], v[66:67], v[40:41]
	v_add_f32_e32 v40, 1.0, v48
	v_rcp_f32_e32 v40, v40
	v_mul_f32_e32 v41, 0xbfb8aa3b, v19
	v_cndmask_b32_e64 v43, v43, v103, s[10:11]
	v_exp_f32_e32 v41, v41
	v_cndmask_b32_e64 v47, v47, v99, s[12:13]
	v_pk_fma_f32 v[42:43], v[72:73], v[42:43], v[76:77]
	v_mul_f32_e32 v18, v18, v40
	v_pk_fma_f32 v[42:43], v[68:69], v[46:47], v[42:43]
	v_mul_f32_e32 v40, 0xbfb8aa3b, v16
	v_pk_fma_f32 v[36:37], v[36:37], v[64:65], v[42:43]
	v_exp_f32_e32 v40, v40
	v_mul_f32_e32 v18, v18, v36
	v_add_f32_e32 v36, 1.0, v41
	v_rcp_f32_e32 v36, v36
	v_mul_f32_e32 v41, 0xbfb8aa3b, v17
	v_exp_f32_e32 v41, v41
	v_mul_f32_e32 v19, v19, v36
	v_add_f32_e32 v36, 1.0, v40
	v_rcp_f32_e32 v36, v36
	v_add_f32_e32 v40, 1.0, v41
	v_rcp_f32_e32 v40, v40
	v_mul_f32_e32 v19, v19, v37
	v_mul_f32_e32 v16, v16, v36
	v_mul_f32_e32 v36, v16, v38
	v_mul_f32_e32 v16, v17, v40
	v_mul_f32_e32 v17, v16, v39
	v_cvt_pk_bf16_f32 v16, v18, v19
	v_cvt_pk_bf16_f32 v17, v36, v17
	global_store_dwordx2 v[108:109], v[16:17], off offset:8
	v_mov_b32_e32 v16, v161
	v_mov_b32_dpp v42, v34 row_ror:1 row_mask:0xf bank_mask:0xf
	v_lshlrev_b32_e32 v16, 2, v16
	v_add_u32_e32 v36, v142, v16
	v_add_u32_e32 v16, s62, v16
	ds_read2_b32 v[40:41], v16 offset0:62 offset1:63
	ds_read_b128 v[16:19], v36 offset:16
	ds_read_b128 v[36:39], v36 offset:272
	v_mov_b32_dpp v46, v34 row_ror:2 row_mask:0xf bank_mask:0xf
	v_mov_b32_dpp v47, v35 row_ror:2 row_mask:0xf bank_mask:0xf
	s_waitcnt lgkmcnt(0)
; #define LAS __attribute__((address_space(3)))
; __device__ __forceinline__ unsigned cvt_pk_bf16(float lo, float hi) { unsigned r; asm volatile("v_cvt_pk_bf16_f32 %0, %1, %2" : "=v"(r) : "v"(lo), "v"(hi)); return r; }
;     __device__ __forceinline__ void operator()(f32x4 (&acc)[2][2][4][2], const Unit& u, int wr, int wc, int fr, int fq) const {
;     ...
;                 for (int m = 0; m < 4; ++m) {
;                     f32x4 gv[2];
; #pragma unroll
;                     for (int bj = 0; bj < 2; ++bj) {
;                         const f32x4 cur = acc[ai][bj][m][n]; f32x4 p1 = ror4(cur, 1), p2 = ror4(cur, 2);
;                         if (m > 0) { const f32x4 pv = acc[ai][bj][m - 1][n]; const f32x4 q1 = ror4(pv, 1), q2 = ror4(pv, 2);
; #pragma unroll
;                             for (int e = 0; e < 4; ++e) { p1[e] = (fr == 0) ? q1[e] : p1[e]; p2[e] = (fr < 2) ? q2[e] : p2[e]; } }
;                         else { f32x4 h14 = (f32x4){0.f, 0.f, 0.f, 0.f}, h15 = h14;
;                             if (!(wr == 0 && ai == 0)) { const int sai = (wr == 1) ? ai : 0, swr = (wr == 1) ? 0 : 1; const int ox = opq(0);
;                                 const LAS float* hp = hl + (((((sai * 2 + swr) * 4 + wc) * 2 + 0) * 2 + bj) * 32 + 8 * fq + 4 * n) + ox;
;                                 const float r14 = rsL[sai * 128 + swr * 64 + 62 + ox], r15 = rsL[sai * 128 + swr * 64 + 63 + ox];
;                                 h14 = *(const LAS f32x4*)hp * r14; h15 = *(const LAS f32x4*)(hp + 64) * r15; }
; #pragma unroll
;                             for (int e = 0; e < 4; ++e) { p1[e] = (fr == 0) ? h15[e] : p1[e]; p2[e] = (fr == 0) ? h14[e] : ((fr == 1) ? h15[e] : p2[e]); } }
;                         const f32x4 w0 = bj ? wv0 : wg0, w1 = bj ? wv1 : wg1, w2 = bj ? wv2 : wg2, bb = bj ? bv : bg;
;                         gv[bj] = bb + w0 * p2 + w1 * p1 + w2 * cur;
;                     }
;                     float o[4];
; #pragma unroll
;                     for (int e = 0; e < 4; ++e) o[e] = gv[0][e] * sigm(gv[0][e]) * gv[1][e];
;                     u32x2 w; w.x = cvt_pk_bf16(o[0], o[1]); w.y = cvt_pk_bf16(o[2], o[3]);
;                     const bool edge = (wr == 0 && ai == 0 && m == 0 && fr < 2 && !seq0);
;                     if (!edge) *(u32x2*)(act + (size_t)(row0 + ai * 128 + m * 16) * DFF + colg0 + 4 * n) = w;
	v_pk_mul_f32 v[36:37], v[36:37], v[40:41] op_sel:[0,1]
	v_pk_mul_f32 v[18:19], v[18:19], v[40:41] op_sel_hi:[1,0]
	v_pk_mul_f32 v[16:17], v[16:17], v[40:41] op_sel_hi:[1,0]
	v_pk_mul_f32 v[38:39], v[38:39], v[40:41] op_sel:[0,1]
	v_cndmask_b32_e64 v40, v42, v36, s[12:13]
	v_cndmask_b32_e64 v36, v46, v36, s[14:15]
	v_mov_b32_dpp v43, v35 row_ror:1 row_mask:0xf bank_mask:0xf
	v_cndmask_b32_e64 v16, v36, v16, s[12:13]
	v_cndmask_b32_e64 v36, v47, v37, s[14:15]
	v_mov_b32_dpp v44, v32 row_ror:1 row_mask:0xf bank_mask:0xf
	v_mov_b32_dpp v48, v32 row_ror:2 row_mask:0xf bank_mask:0xf
	v_mov_b32_dpp v49, v33 row_ror:2 row_mask:0xf bank_mask:0xf
	v_cndmask_b32_e64 v17, v36, v17, s[12:13]
	v_mov_b32_dpp v45, v33 row_ror:1 row_mask:0xf bank_mask:0xf
	v_cndmask_b32_e64 v41, v43, v37, s[12:13]
	v_pk_fma_f32 v[16:17], v[88:89], v[16:17], v[92:93]
	v_cndmask_b32_e64 v36, v44, v38, s[12:13]
	v_cndmask_b32_e64 v37, v48, v38, s[14:15]
	v_cndmask_b32_e64 v38, v49, v39, s[14:15]
	v_pk_fma_f32 v[16:17], v[80:81], v[40:41], v[16:17]
	v_cndmask_b32_e64 v18, v37, v18, s[12:13]
	v_cndmask_b32_e64 v37, v45, v39, s[12:13]
	v_cndmask_b32_e64 v19, v38, v19, s[12:13]
	v_pk_fma_f32 v[38:39], v[34:35], v[84:85], v[16:17]
	v_mov_b32_e32 v16, v161
	v_pk_fma_f32 v[18:19], v[90:91], v[18:19], v[94:95]
	v_mov_b32_dpp v50, v28 row_ror:1 row_mask:0xf bank_mask:0xf
	v_pk_fma_f32 v[18:19], v[82:83], v[36:37], v[18:19]
	v_lshlrev_b32_e32 v16, 2, v16
	v_pk_fma_f32 v[36:37], v[32:33], v[86:87], v[18:19]
	v_add_u32_e32 v32, v142, v16
	v_add_u32_e32 v16, s62, v16
	ds_read2_b32 v[40:41], v16 offset0:62 offset1:63
	ds_read_b128 v[16:19], v32 offset:144
	ds_read_b128 v[32:35], v32 offset:400
	v_mov_b32_dpp v54, v28 row_ror:2 row_mask:0xf bank_mask:0xf
	v_mov_b32_dpp v55, v29 row_ror:2 row_mask:0xf bank_mask:0xf
	s_waitcnt lgkmcnt(0)
	v_pk_mul_f32 v[32:33], v[32:33], v[40:41] op_sel:[0,1]
	v_mov_b32_dpp v51, v29 row_ror:1 row_mask:0xf bank_mask:0xf
	v_mov_b32_dpp v52, v30 row_ror:1 row_mask:0xf bank_mask:0xf
	v_mov_b32_dpp v56, v30 row_ror:2 row_mask:0xf bank_mask:0xf
	v_mov_b32_dpp v57, v31 row_ror:2 row_mask:0xf bank_mask:0xf
	v_pk_mul_f32 v[18:19], v[18:19], v[40:41] op_sel_hi:[1,0]
	v_pk_mul_f32 v[16:17], v[16:17], v[40:41] op_sel_hi:[1,0]
	v_pk_mul_f32 v[34:35], v[34:35], v[40:41] op_sel:[0,1]
	v_cndmask_b32_e64 v40, v50, v32, s[12:13]
	v_cndmask_b32_e64 v32, v54, v32, s[14:15]
	v_cndmask_b32_e64 v16, v32, v16, s[12:13]
	v_cndmask_b32_e64 v32, v55, v33, s[14:15]
	v_cndmask_b32_e64 v41, v51, v33, s[12:13]
	v_cndmask_b32_e64 v17, v32, v17, s[12:13]
	v_cndmask_b32_e64 v32, v52, v34, s[12:13]
	v_cndmask_b32_e64 v33, v56, v34, s[14:15]
	v_cndmask_b32_e64 v34, v57, v35, s[14:15]
	v_cndmask_b32_e64 v19, v34, v19, s[12:13]
	v_mul_f32_e32 v34, 0xbfb8aa3b, v38
	v_mov_b32_dpp v53, v31 row_ror:1 row_mask:0xf bank_mask:0xf
	v_exp_f32_e32 v34, v34
	v_cndmask_b32_e64 v18, v33, v18, s[12:13]
	v_cndmask_b32_e64 v33, v53, v35, s[12:13]
	v_pk_fma_f32 v[18:19], v[74:75], v[18:19], v[78:79]
	v_pk_fma_f32 v[16:17], v[72:73], v[16:17], v[76:77]
	v_pk_fma_f32 v[18:19], v[70:71], v[32:33], v[18:19]
	v_pk_fma_f32 v[16:17], v[68:69], v[40:41], v[16:17]
	v_pk_fma_f32 v[18:19], v[30:31], v[66:67], v[18:19]
	v_add_f32_e32 v30, 1.0, v34
	v_rcp_f32_e32 v30, v30
	v_mul_f32_e32 v31, 0xbfb8aa3b, v39
	v_exp_f32_e32 v31, v31
	v_pk_fma_f32 v[16:17], v[28:29], v[64:65], v[16:17]
	v_mul_f32_e32 v29, 0xbfb8aa3b, v36
	v_mul_f32_e32 v28, v38, v30
	v_exp_f32_e32 v29, v29
	v_mul_f32_e32 v30, 0xbfb8aa3b, v37
	v_exp_f32_e32 v30, v30
	v_mul_f32_e32 v16, v28, v16
	v_add_f32_e32 v28, 1.0, v31
	v_rcp_f32_e32 v28, v28
	v_add_f32_e32 v29, 1.0, v29
	v_rcp_f32_e32 v29, v29
	v_add_f32_e32 v30, 1.0, v30
	v_rcp_f32_e32 v30, v30
	v_mul_f32_e32 v28, v39, v28
	v_mul_f32_e32 v17, v28, v17
	v_mul_f32_e32 v28, v36, v29
	v_mul_f32_e32 v18, v28, v18
	v_mul_f32_e32 v28, v37, v30
	v_mul_f32_e32 v19, v28, v19
	v_cvt_pk_bf16_f32 v16, v16, v17
	v_cvt_pk_bf16_f32 v17, v18, v19
	global_store_dwordx2 v[110:111], v[16:17], off offset:8
	v_mov_b32_dpp v36, v24 row_ror:2 row_mask:0xf bank_mask:0xf
	v_mov_b32_dpp v37, v25 row_ror:2 row_mask:0xf bank_mask:0xf
	v_mov_b32_dpp v32, v24 row_ror:1 row_mask:0xf bank_mask:0xf
	v_mov_b32_dpp v33, v25 row_ror:1 row_mask:0xf bank_mask:0xf
	v_mov_b32_dpp v38, v26 row_ror:2 row_mask:0xf bank_mask:0xf
	v_mov_b32_dpp v39, v27 row_ror:2 row_mask:0xf bank_mask:0xf
	v_cndmask_b32_e64 v18, v36, v46, s[10:11]
	v_cndmask_b32_e64 v19, v37, v47, s[10:11]
	v_mov_b32_dpp v34, v26 row_ror:1 row_mask:0xf bank_mask:0xf
	v_mov_b32_dpp v35, v27 row_ror:1 row_mask:0xf bank_mask:0xf
	v_cndmask_b32_e64 v30, v32, v42, s[12:13]
	v_cndmask_b32_e64 v31, v33, v43, s[12:13]
	v_pk_fma_f32 v[18:19], v[88:89], v[18:19], v[92:93]
	v_mov_b32_dpp v46, v20 row_ror:2 row_mask:0xf bank_mask:0xf
	v_mov_b32_dpp v47, v21 row_ror:2 row_mask:0xf bank_mask:0xf
	v_cndmask_b32_e64 v17, v39, v49, s[10:11]
	v_cndmask_b32_e64 v16, v38, v48, s[10:11]
	v_pk_fma_f32 v[18:19], v[80:81], v[30:31], v[18:19]
	v_mov_b32_dpp v42, v20 row_ror:1 row_mask:0xf bank_mask:0xf
	v_mov_b32_dpp v43, v21 row_ror:1 row_mask:0xf bank_mask:0xf
	v_cndmask_b32_e64 v29, v35, v45, s[12:13]
	v_cndmask_b32_e64 v28, v34, v44, s[12:13]
	v_pk_fma_f32 v[16:17], v[90:91], v[16:17], v[94:95]
	v_pk_fma_f32 v[18:19], v[24:25], v[84:85], v[18:19]
	v_cndmask_b32_e64 v25, v47, v57, s[10:11]
	v_cndmask_b32_e64 v24, v46, v56, s[10:11]
	v_pk_fma_f32 v[16:17], v[82:83], v[28:29], v[16:17]
	v_cndmask_b32_e64 v29, v43, v53, s[12:13]
	v_cndmask_b32_e64 v28, v42, v52, s[12:13]
	v_pk_fma_f32 v[24:25], v[74:75], v[24:25], v[78:79]
	v_mov_b32_dpp v44, v22 row_ror:2 row_mask:0xf bank_mask:0xf
; #define LAS __attribute__((address_space(3)))
; __device__ __forceinline__ unsigned cvt_pk_bf16(float lo, float hi) { unsigned r; asm volatile("v_cvt_pk_bf16_f32 %0, %1, %2" : "=v"(r) : "v"(lo), "v"(hi)); return r; }
;     __device__ __forceinline__ void operator()(f32x4 (&acc)[2][2][4][2], const Unit& u, int wr, int wc, int fr, int fq) const {
;     ...
;                 for (int m = 0; m < 4; ++m) {
;                     f32x4 gv[2];
; #pragma unroll
;                     for (int bj = 0; bj < 2; ++bj) {
;                         const f32x4 cur = acc[ai][bj][m][n]; f32x4 p1 = ror4(cur, 1), p2 = ror4(cur, 2);
;                         if (m > 0) { const f32x4 pv = acc[ai][bj][m - 1][n]; const f32x4 q1 = ror4(pv, 1), q2 = ror4(pv, 2);
; #pragma unroll
;                             for (int e = 0; e < 4; ++e) { p1[e] = (fr == 0) ? q1[e] : p1[e]; p2[e] = (fr < 2) ? q2[e] : p2[e]; } }
;                         else { f32x4 h14 = (f32x4){0.f, 0.f, 0.f, 0.f}, h15 = h14;
;                             if (!(wr == 0 && ai == 0)) { const int sai = (wr == 1) ? ai : 0, swr = (wr == 1) ? 0 : 1; const int ox = opq(0);
;                                 const LAS float* hp = hl + (((((sai * 2 + swr) * 4 + wc) * 2 + 0) * 2 + bj) * 32 + 8 * fq + 4 * n) + ox;
;                                 const float r14 = rsL[sai * 128 + swr * 64 + 62 + ox], r15 = rsL[sai * 128 + swr * 64 + 63 + ox];
;                                 h14 = *(const LAS f32x4*)hp * r14; h15 = *(const LAS f32x4*)(hp + 64) * r15; }
; #pragma unroll
;                             for (int e = 0; e < 4; ++e) { p1[e] = (fr == 0) ? h15[e] : p1[e]; p2[e] = (fr == 0) ? h14[e] : ((fr == 1) ? h15[e] : p2[e]); } }
;                         const f32x4 w0 = bj ? wv0 : wg0, w1 = bj ? wv1 : wg1, w2 = bj ? wv2 : wg2, bb = bj ? bv : bg;
;                         gv[bj] = bb + w0 * p2 + w1 * p1 + w2 * cur;
;                     }
;                     float o[4];
; #pragma unroll
;                     for (int e = 0; e < 4; ++e) o[e] = gv[0][e] * sigm(gv[0][e]) * gv[1][e];
;                     u32x2 w; w.x = cvt_pk_bf16(o[0], o[1]); w.y = cvt_pk_bf16(o[2], o[3]);
;                     const bool edge = (wr == 0 && ai == 0 && m == 0 && fr < 2 && !seq0);
;                     if (!edge) *(u32x2*)(act + (size_t)(row0 + ai * 128 + m * 16) * DFF + colg0 + 4 * n) = w;
	v_pk_fma_f32 v[24:25], v[70:71], v[28:29], v[24:25]
	v_mov_b32_dpp v45, v23 row_ror:2 row_mask:0xf bank_mask:0xf
	v_pk_fma_f32 v[20:21], v[20:21], v[66:67], v[24:25]
	v_mul_f32_e32 v24, 0xbfb8aa3b, v18
	v_exp_f32_e32 v24, v24
	v_mov_b32_dpp v40, v22 row_ror:1 row_mask:0xf bank_mask:0xf
	v_mov_b32_dpp v41, v23 row_ror:1 row_mask:0xf bank_mask:0xf
	v_add_f32_e32 v24, 1.0, v24
	v_rcp_f32_e32 v24, v24
	v_pk_fma_f32 v[16:17], v[26:27], v[86:87], v[16:17]
	v_cndmask_b32_e64 v26, v44, v54, s[10:11]
	v_cndmask_b32_e64 v27, v45, v55, s[10:11]
	v_cndmask_b32_e64 v30, v40, v50, s[12:13]
	v_cndmask_b32_e64 v31, v41, v51, s[12:13]
	v_pk_fma_f32 v[26:27], v[72:73], v[26:27], v[76:77]
	v_mul_f32_e32 v18, v18, v24
	v_pk_fma_f32 v[26:27], v[68:69], v[30:31], v[26:27]
	s_nop 0
	v_pk_fma_f32 v[22:23], v[22:23], v[64:65], v[26:27]
	s_nop 0
	v_mul_f32_e32 v18, v18, v22
	v_mul_f32_e32 v22, 0xbfb8aa3b, v19
	v_exp_f32_e32 v22, v22
	s_nop 0
	v_add_f32_e32 v22, 1.0, v22
	v_rcp_f32_e32 v22, v22
	s_nop 0
	v_mul_f32_e32 v19, v19, v22
	v_mul_f32_e32 v22, 0xbfb8aa3b, v16
	v_exp_f32_e32 v22, v22
	v_mul_f32_e32 v19, v19, v23
	v_add_f32_e32 v22, 1.0, v22
	v_rcp_f32_e32 v22, v22
	s_nop 0
	v_mul_f32_e32 v16, v16, v22
	v_mul_f32_e32 v20, v16, v20
	v_mul_f32_e32 v16, 0xbfb8aa3b, v17
	v_exp_f32_e32 v16, v16
	s_nop 0
	v_add_f32_e32 v16, 1.0, v16
	v_rcp_f32_e32 v16, v16
	s_nop 0
	v_mul_f32_e32 v16, v17, v16
	v_mul_f32_e32 v17, v16, v21
	v_cvt_pk_bf16_f32 v16, v18, v19
	v_cvt_pk_bf16_f32 v17, v20, v17
	global_store_dwordx2 v[112:113], v[16:17], off offset:8
	v_mov_b32_dpp v30, v12 row_ror:2 row_mask:0xf bank_mask:0xf
	v_mov_b32_dpp v31, v13 row_ror:2 row_mask:0xf bank_mask:0xf
	v_mov_b32_dpp v26, v12 row_ror:1 row_mask:0xf bank_mask:0xf
	v_mov_b32_dpp v27, v13 row_ror:1 row_mask:0xf bank_mask:0xf
	v_mov_b32_dpp v28, v14 row_ror:2 row_mask:0xf bank_mask:0xf
	v_mov_b32_dpp v29, v15 row_ror:2 row_mask:0xf bank_mask:0xf
	v_cndmask_b32_e64 v17, v31, v39, s[10:11]
	v_cndmask_b32_e64 v16, v30, v38, s[10:11]
	v_mov_b32_dpp v24, v14 row_ror:1 row_mask:0xf bank_mask:0xf
	v_mov_b32_dpp v25, v15 row_ror:1 row_mask:0xf bank_mask:0xf
	v_cndmask_b32_e64 v21, v27, v35, s[12:13]
	v_cndmask_b32_e64 v20, v26, v34, s[12:13]
	v_pk_fma_f32 v[16:17], v[90:91], v[16:17], v[94:95]
	v_mov_b32_dpp v38, v10 row_ror:2 row_mask:0xf bank_mask:0xf
	v_mov_b32_dpp v39, v11 row_ror:2 row_mask:0xf bank_mask:0xf
	v_cndmask_b32_e64 v18, v28, v36, s[10:11]
	v_cndmask_b32_e64 v19, v29, v37, s[10:11]
	v_pk_fma_f32 v[16:17], v[82:83], v[20:21], v[16:17]
	v_mov_b32_dpp v34, v10 row_ror:1 row_mask:0xf bank_mask:0xf
	v_mov_b32_dpp v35, v11 row_ror:1 row_mask:0xf bank_mask:0xf
	v_cndmask_b32_e64 v22, v24, v32, s[12:13]
	v_cndmask_b32_e64 v23, v25, v33, s[12:13]
	v_pk_fma_f32 v[18:19], v[88:89], v[18:19], v[92:93]
	v_pk_fma_f32 v[12:13], v[12:13], v[86:87], v[16:17]
	v_cndmask_b32_e64 v17, v39, v47, s[10:11]
	v_cndmask_b32_e64 v16, v38, v46, s[10:11]
	v_pk_fma_f32 v[18:19], v[80:81], v[22:23], v[18:19]
	v_cndmask_b32_e64 v21, v35, v43, s[12:13]
	v_cndmask_b32_e64 v20, v34, v42, s[12:13]
	v_pk_fma_f32 v[16:17], v[74:75], v[16:17], v[78:79]
	v_pk_fma_f32 v[14:15], v[14:15], v[84:85], v[18:19]
	v_pk_fma_f32 v[16:17], v[70:71], v[20:21], v[16:17]
	v_mov_b32_dpp v36, v8 row_ror:2 row_mask:0xf bank_mask:0xf
	v_pk_fma_f32 v[10:11], v[10:11], v[66:67], v[16:17]
	v_mul_f32_e32 v16, 0xbfb8aa3b, v14
	v_exp_f32_e32 v16, v16
	v_mov_b32_dpp v37, v9 row_ror:2 row_mask:0xf bank_mask:0xf
	v_mov_b32_dpp v32, v8 row_ror:1 row_mask:0xf bank_mask:0xf
	v_mov_b32_dpp v33, v9 row_ror:1 row_mask:0xf bank_mask:0xf
	v_add_f32_e32 v16, 1.0, v16
	v_rcp_f32_e32 v16, v16
	v_cndmask_b32_e64 v18, v36, v44, s[10:11]
	v_cndmask_b32_e64 v19, v37, v45, s[10:11]
	v_cndmask_b32_e64 v22, v32, v40, s[12:13]
	v_cndmask_b32_e64 v23, v33, v41, s[12:13]
	v_pk_fma_f32 v[18:19], v[72:73], v[18:19], v[76:77]
	v_mul_f32_e32 v14, v14, v16
	v_pk_fma_f32 v[18:19], v[68:69], v[22:23], v[18:19]
; template <class Epi>
; __device__ __forceinline__ void gemm_phase(LAS unsigned char* lds, const Gemm g, const StaticOrder& S, const Epi& E) {
;     ...
;         if (wr == 0) PG8_BAR;
;         E(acc, cur, wr, wc, fr, fq);
;         if (!has_next) break;
; #pragma unroll
;     __device__ __forceinline__ void operator()(f32x4 (&acc)[2][2][4][2], const Unit& u, int wr, int wc, int fr, int fq) const {
;     ...
;                 for (int m = 0; m < 4; ++m) {
;                     f32x4 gv[2];
; #pragma unroll
;                     for (int bj = 0; bj < 2; ++bj) {
;                         const f32x4 cur = acc[ai][bj][m][n]; f32x4 p1 = ror4(cur, 1), p2 = ror4(cur, 2);
;                         if (m > 0) { const f32x4 pv = acc[ai][bj][m - 1][n]; const f32x4 q1 = ror4(pv, 1), q2 = ror4(pv, 2);
; #pragma unroll
;                             for (int e = 0; e < 4; ++e) { p1[e] = (fr == 0) ? q1[e] : p1[e]; p2[e] = (fr < 2) ? q2[e] : p2[e]; } }
;                         else { f32x4 h14 = (f32x4){0.f, 0.f, 0.f, 0.f}, h15 = h14;
;                             if (!(wr == 0 && ai == 0)) { const int sai = (wr == 1) ? ai : 0, swr = (wr == 1) ? 0 : 1; const int ox = opq(0);
;                                 const LAS float* hp = hl + (((((sai * 2 + swr) * 4 + wc) * 2 + 0) * 2 + bj) * 32 + 8 * fq + 4 * n) + ox;
;                                 const float r14 = rsL[sai * 128 + swr * 64 + 62 + ox], r15 = rsL[sai * 128 + swr * 64 + 63 + ox];
;                                 h14 = *(const LAS f32x4*)hp * r14; h15 = *(const LAS f32x4*)(hp + 64) * r15; }
; #pragma unroll
;                             for (int e = 0; e < 4; ++e) { p1[e] = (fr == 0) ? h15[e] : p1[e]; p2[e] = (fr == 0) ? h14[e] : ((fr == 1) ? h15[e] : p2[e]); } }
;                         const f32x4 w0 = bj ? wv0 : wg0, w1 = bj ? wv1 : wg1, w2 = bj ? wv2 : wg2, bb = bj ? bv : bg;
;                         gv[bj] = bb + w0 * p2 + w1 * p1 + w2 * cur;
;                     }
;                     float o[4];
; #pragma unroll
;                     for (int e = 0; e < 4; ++e) o[e] = gv[0][e] * sigm(gv[0][e]) * gv[1][e];
;                     u32x2 w; w.x = cvt_pk_bf16(o[0], o[1]); w.y = cvt_pk_bf16(o[2], o[3]);
;                     const bool edge = (wr == 0 && ai == 0 && m == 0 && fr < 2 && !seq0);
;                     if (!edge) *(u32x2*)(act + (size_t)(row0 + ai * 128 + m * 16) * DFF + colg0 + 4 * n) = w;
	s_nop 0
	v_pk_fma_f32 v[8:9], v[8:9], v[64:65], v[18:19]
	s_nop 0
	v_mul_f32_e32 v8, v14, v8
	v_mul_f32_e32 v14, 0xbfb8aa3b, v15
	v_exp_f32_e32 v14, v14
	s_nop 0
	v_add_f32_e32 v14, 1.0, v14
	v_rcp_f32_e32 v14, v14
	s_nop 0
	v_mul_f32_e32 v14, v15, v14
	v_mul_f32_e32 v9, v14, v9
	v_mul_f32_e32 v14, 0xbfb8aa3b, v12
	v_exp_f32_e32 v14, v14
	v_cvt_pk_bf16_f32 v8, v8, v9
	s_nop 0
	v_add_f32_e32 v14, 1.0, v14
	v_rcp_f32_e32 v14, v14
	s_nop 0
	v_mul_f32_e32 v12, v12, v14
	v_mul_f32_e32 v10, v12, v10
	v_mul_f32_e32 v12, 0xbfb8aa3b, v13
	v_exp_f32_e32 v12, v12
	s_nop 0
	v_add_f32_e32 v12, 1.0, v12
	v_rcp_f32_e32 v12, v12
	s_nop 0
	v_mul_f32_e32 v12, v13, v12
	v_mul_f32_e32 v11, v12, v11
	v_cvt_pk_bf16_f32 v9, v10, v11
	global_store_dwordx2 v[114:115], v[8:9], off offset:8
	v_mov_b32_dpp v8, v4 row_ror:2 row_mask:0xf bank_mask:0xf
	v_mov_b32_dpp v14, v6 row_ror:2 row_mask:0xf bank_mask:0xf
	v_mov_b32_dpp v9, v7 row_ror:2 row_mask:0xf bank_mask:0xf
	v_mov_b32_dpp v12, v4 row_ror:1 row_mask:0xf bank_mask:0xf
	v_mov_b32_dpp v16, v6 row_ror:1 row_mask:0xf bank_mask:0xf
	v_mov_b32_dpp v13, v7 row_ror:1 row_mask:0xf bank_mask:0xf
	v_mov_b32_dpp v11, v5 row_ror:2 row_mask:0xf bank_mask:0xf
	v_mov_b32_dpp v15, v5 row_ror:1 row_mask:0xf bank_mask:0xf
	v_cndmask_b32_e64 v9, v9, v31, s[10:11]
	v_cndmask_b32_e64 v10, v8, v28, s[10:11]
	v_cndmask_b32_e64 v8, v14, v30, s[10:11]
	v_cndmask_b32_e64 v11, v11, v29, s[10:11]
	v_cndmask_b32_e64 v13, v13, v27, s[12:13]
	v_cndmask_b32_e64 v14, v12, v24, s[12:13]
	v_cndmask_b32_e64 v12, v16, v26, s[12:13]
	v_pk_fma_f32 v[8:9], v[90:91], v[8:9], v[94:95]
	v_cndmask_b32_e64 v15, v15, v25, s[12:13]
	v_pk_fma_f32 v[10:11], v[88:89], v[10:11], v[92:93]
	v_pk_fma_f32 v[8:9], v[82:83], v[12:13], v[8:9]
	v_pk_fma_f32 v[10:11], v[80:81], v[14:15], v[10:11]
	v_pk_fma_f32 v[6:7], v[6:7], v[86:87], v[8:9]
	v_mov_b32_dpp v12, v0 row_ror:1 row_mask:0xf bank_mask:0xf
	v_mov_b32_dpp v16, v2 row_ror:1 row_mask:0xf bank_mask:0xf
	v_mov_b32_dpp v8, v0 row_ror:2 row_mask:0xf bank_mask:0xf
	v_mov_b32_dpp v14, v2 row_ror:2 row_mask:0xf bank_mask:0xf
	v_pk_fma_f32 v[4:5], v[4:5], v[84:85], v[10:11]
	v_mov_b32_dpp v9, v3 row_ror:2 row_mask:0xf bank_mask:0xf
	v_cndmask_b32_e64 v10, v8, v36, s[10:11]
	v_cndmask_b32_e64 v8, v14, v38, s[10:11]
	v_cndmask_b32_e64 v14, v12, v32, s[12:13]
	v_cndmask_b32_e64 v12, v16, v34, s[12:13]
	v_mul_f32_e32 v16, 0xbfb8aa3b, v4
	v_mov_b32_dpp v13, v3 row_ror:1 row_mask:0xf bank_mask:0xf
	v_exp_f32_e32 v16, v16
	v_cndmask_b32_e64 v9, v9, v39, s[10:11]
	v_cndmask_b32_e64 v13, v13, v35, s[12:13]
	v_pk_fma_f32 v[8:9], v[74:75], v[8:9], v[78:79]
	v_mov_b32_dpp v11, v1 row_ror:2 row_mask:0xf bank_mask:0xf
	v_pk_fma_f32 v[8:9], v[70:71], v[12:13], v[8:9]
	v_mov_b32_dpp v15, v1 row_ror:1 row_mask:0xf bank_mask:0xf
	v_pk_fma_f32 v[2:3], v[2:3], v[66:67], v[8:9]
	v_add_f32_e32 v8, 1.0, v16
	v_rcp_f32_e32 v8, v8
	v_mul_f32_e32 v9, 0xbfb8aa3b, v5
	v_cndmask_b32_e64 v11, v11, v37, s[10:11]
	v_exp_f32_e32 v9, v9
	v_cndmask_b32_e64 v15, v15, v33, s[12:13]
	v_pk_fma_f32 v[10:11], v[72:73], v[10:11], v[76:77]
	v_mul_f32_e32 v4, v4, v8
	v_pk_fma_f32 v[10:11], v[68:69], v[14:15], v[10:11]
	v_mul_f32_e32 v8, 0xbfb8aa3b, v6
	v_pk_fma_f32 v[0:1], v[0:1], v[64:65], v[10:11]
	v_exp_f32_e32 v8, v8
	v_mul_f32_e32 v0, v4, v0
	v_add_f32_e32 v4, 1.0, v9
	v_rcp_f32_e32 v4, v4
	v_mul_f32_e32 v9, 0xbfb8aa3b, v7
	v_exp_f32_e32 v9, v9
	v_mul_f32_e32 v4, v5, v4
	v_add_f32_e32 v5, 1.0, v8
	v_rcp_f32_e32 v5, v5
	v_add_f32_e32 v8, 1.0, v9
	v_rcp_f32_e32 v8, v8
	v_mul_f32_e32 v1, v4, v1
	v_mul_f32_e32 v4, v6, v5
	v_mul_f32_e32 v2, v4, v2
	v_mul_f32_e32 v4, v7, v8
	v_mul_f32_e32 v3, v4, v3
	v_cvt_pk_bf16_f32 v0, v0, v1
	v_cvt_pk_bf16_f32 v1, v2, v3
	global_store_dwordx2 v[96:97], v[0:1], off offset:8
	s_andn2_b64 vcc, exec, s[8:9]
	s_mov_b64 s[8:9], -1
	s_cbranch_vccnz .LBB0_1023
	s_andn2_b64 vcc, exec, s[42:43]
	s_cbranch_vccnz .LBB0_1022
	s_barrier
	s_branch .LBB0_1022
